# ffn_up epilogue: conv weight/bias vectors loaded before the accumulator hand-off (pass 1 during pass 0), no vmcnt waits inside row blocks
# speedup vs baseline: 1.0185x; 1.0015x over previous
.LBB0_1012:
	v_mov_b32_e32 v155, v128
	s_nop 1
	v_readlane_b32 s38, v252, 2
	v_readlane_b32 s39, v252, 3
	v_readlane_b32 s40, v252, 4
	v_readlane_b32 s41, v252, 5
	v_lshlrev_b32_sdwa v240, v151, v155 dst_sel:DWORD dst_unused:UNUSED_PAD src0_sel:DWORD src1_sel:BYTE_0
	v_and_b32_e32 v240, 56, v240
	v_lshl_or_b32 v240, s4, 7, v240
	v_ashrrev_i32_e32 v241, 31, v240
	v_lshlrev_b64 v[240:241], 2, v[240:241]
	v_lshl_add_u64 v[232:233], s[38:39], 0, v[240:241]
	v_lshl_add_u64 v[234:235], s[8:9], 0, v[240:241]
	v_lshl_add_u64 v[236:237], s[10:11], 0, v[240:241]
	v_lshl_add_u64 v[238:239], s[40:41], 0, v[240:241]
	global_load_dwordx4 v[200:203], v[232:233], off
	global_load_dwordx4 v[204:207], v[232:233], off offset:16
	global_load_dwordx4 v[208:211], v[234:235], off
	global_load_dwordx4 v[212:215], v[234:235], off offset:16
	global_load_dwordx4 v[216:219], v[236:237], off
	global_load_dwordx4 v[220:223], v[236:237], off offset:16
	global_load_dwordx4 v[224:227], v[238:239], off
	global_load_dwordx4 v[228:231], v[238:239], off offset:16
	s_mov_b32 s0, 0x12000
	v_and_b32_e32 v134, 15, v155
	v_ashrrev_i32_e32 v156, 8, v155
	v_mul_u32_u24_e32 v134, 0x210, v134
	v_lshlrev_b32_e32 v157, 1, v155
	v_mad_i32_i24 v134, v156, s0, v134
	v_and_b32_e32 v157, 0x180, v157
	v_and_b32_e32 v158, 48, v155
	v_add3_u32 v134, v134, v157, v158
	ds_write_b128 v134, v[124:127]
	ds_write_b128 v134, v[120:123] offset:64
	ds_write_b128 v134, v[116:119] offset:8448
	ds_write_b128 v134, v[112:115] offset:8512
	ds_write_b128 v134, v[108:111] offset:16896
	ds_write_b128 v134, v[104:107] offset:16960
	ds_write_b128 v134, v[100:103] offset:25344
	ds_write_b128 v134, v[96:99] offset:25408
	ds_write_b128 v134, v[92:95] offset:33792
	ds_write_b128 v134, v[88:91] offset:33856
	ds_write_b128 v134, v[84:87] offset:42240
	ds_write_b128 v134, v[80:83] offset:42304
	ds_write_b128 v134, v[76:79] offset:50688
	ds_write_b128 v134, v[72:75] offset:50752
	ds_write_b128 v134, v[68:71] offset:59136
	ds_write_b128 v134, v[64:67] offset:59200
	v_add_u32_e32 v107, s5, v156
	v_cmp_lt_i32_e32 vcc, s13, v107
	s_waitcnt lgkmcnt(0)
	s_barrier
	s_and_saveexec_b64 s[0:1], vcc
	s_xor_b64 s[0:1], exec, s[0:1]
	v_add_u32_e32 v64, 0xffffff78, v107
	v_mul_hi_u32 v65, v64, s12
	v_lshrrev_b32_e32 v65, 1, v65
	v_lshl_add_u32 v116, v65, 8, v149
	v_lshl_add_u32 v65, v65, 1, v65
	v_sub_u32_e32 v102, v64, v65
	s_or_saveexec_b64 s[0:1], s[0:1]
	v_mov_b32_e32 v117, 0x100
	s_xor_b64 exec, exec, s[0:1]
	v_mul_hi_i32 v64, v107, s14
	v_lshrrev_b32_e32 v65, 31, v64
	v_ashrrev_i32_e32 v64, 3, v64
	v_add_u32_e32 v64, v64, v65
	v_lshlrev_b32_e32 v116, 11, v64
	v_lshl_add_u32 v64, v64, 4, v64
	v_sub_u32_e32 v102, v107, v64
	v_mov_b32_e32 v117, 0x800
	s_or_b64 exec, exec, s[0:1]
	v_lshlrev_b32_sdwa v64, v151, v155 dst_sel:DWORD dst_unused:UNUSED_PAD src0_sel:DWORD src1_sel:BYTE_0
	v_and_b32_e32 v103, 56, v64
	v_lshl_or_b32 v96, s4, 7, v103
	v_ashrrev_i32_e32 v97, 31, v96
	v_readlane_b32 s36, v252, 0
	v_lshlrev_b64 v[76:77], 2, v[96:97]
	v_readlane_b32 s38, v252, 2
	v_readlane_b32 s39, v252, 3
	v_readlane_b32 s40, v252, 4
	v_readlane_b32 s41, v252, 5
	v_lshl_add_u64 v[98:99], s[38:39], 0, v[76:77]
	v_lshl_add_u64 v[68:69], s[8:9], 0, v[76:77]
	s_waitcnt vmcnt(0)
	v_mov_b64_e32 v[80:81], v[200:201]
	v_mov_b64_e32 v[82:83], v[202:203]
	v_mov_b64_e32 v[64:65], v[204:205]
	v_mov_b64_e32 v[66:67], v[206:207]
	v_mov_b64_e32 v[84:85], v[208:209]
	v_mov_b64_e32 v[86:87], v[210:211]
	v_mov_b64_e32 v[72:73], v[212:213]
	v_mov_b64_e32 v[74:75], v[214:215]
	v_lshl_add_u64 v[68:69], s[10:11], 0, v[76:77]
	v_lshl_add_u64 v[100:101], s[40:41], 0, v[76:77]
	v_mov_b64_e32 v[88:89], v[216:217]
	v_mov_b64_e32 v[90:91], v[218:219]
	s_nop 0
	v_mov_b64_e32 v[68:69], v[220:221]
	v_mov_b64_e32 v[70:71], v[222:223]
	s_nop 0
	v_mov_b64_e32 v[92:93], v[224:225]
	v_mov_b64_e32 v[94:95], v[226:227]
	v_mov_b64_e32 v[76:77], v[228:229]
	v_mov_b64_e32 v[78:79], v[230:231]
	global_load_dwordx4 v[200:203], v[232:233], off offset:256
	global_load_dwordx4 v[204:207], v[232:233], off offset:272
	global_load_dwordx4 v[208:211], v[234:235], off offset:256
	global_load_dwordx4 v[212:215], v[234:235], off offset:272
	global_load_dwordx4 v[216:219], v[236:237], off offset:256
	global_load_dwordx4 v[220:223], v[236:237], off offset:272
	global_load_dwordx4 v[224:227], v[238:239], off offset:256
	global_load_dwordx4 v[228:231], v[238:239], off offset:272
	v_bfe_u32 v110, v155, 3, 5
	v_lshlrev_b32_e32 v112, 2, v103
	v_mad_u64_u32 v[102:103], s[4:5], v102, s15, -1
	v_mul_i32_i24_e32 v106, 0x12000, v156
	v_mul_u32_u24_e32 v104, 0x210, v110
	v_add_u32_e32 v103, v102, v110
	v_cmp_gt_u32_sdwa s[0:1], v155, v153 src0_sel:BYTE_0 src1_sel:DWORD
	v_add3_u32 v104, v106, v104, v112
	v_cmp_lt_i32_e64 s[4:5], v103, v117
	v_add_u32_e32 v108, 0xfffffdf0, v104
	s_and_b64 s[6:7], s[0:1], s[4:5]
	v_readlane_b32 s37, v252, 1
	v_readlane_b32 s42, v252, 6
	v_readlane_b32 s43, v252, 7
	v_readlane_b32 s44, v252, 8
	v_readlane_b32 s45, v252, 9
	v_readlane_b32 s46, v252, 10
	v_readlane_b32 s47, v252, 11
	v_readlane_b32 s48, v252, 12
	v_readlane_b32 s49, v252, 13
	v_readlane_b32 s50, v252, 14
	v_readlane_b32 s51, v252, 15
	s_and_saveexec_b64 s[4:5], s[6:7]
	s_cbranch_execz .LBB0_1018
	ds_read_b128 v[118:121], v104
	ds_read_b128 v[122:125], v108
	ds_read_b128 v[156:159], v108 offset:16
	ds_read_b128 v[160:163], v104 offset:528
	ds_read_b128 v[164:167], v104 offset:16
	s_waitcnt lgkmcnt(4)
	v_mul_f32_e32 v105, v84, v118
	v_mul_f32_e32 v111, v85, v119
	s_waitcnt lgkmcnt(3)
	v_fmac_f32_e32 v105, v80, v122
	v_fmac_f32_e32 v111, v81, v123
	s_waitcnt lgkmcnt(1)
	v_fmac_f32_e32 v105, v88, v160
	v_fmac_f32_e32 v111, v89, v161
	v_add_f32_e32 v105, v92, v105
	v_add_f32_e32 v111, v93, v111
	v_mul_f32_e32 v109, 0xbfb8aa3b, v105
	v_mul_f32_e32 v113, 0xbfb8aa3b, v111
	v_exp_f32_e32 v109, v109
	v_exp_f32_e32 v113, v113
	v_mul_f32_e32 v114, v87, v121
	v_fmac_f32_e32 v114, v83, v125
	v_add_f32_e32 v109, 1.0, v109
	v_add_f32_e32 v113, 1.0, v113
	v_rcp_f32_e32 v109, v109
	v_rcp_f32_e32 v113, v113
	v_fmac_f32_e32 v114, v91, v163
	v_add_f32_e32 v114, v95, v114
	v_mul_f32_e32 v105, v105, v109
	v_mul_f32_e32 v109, v111, v113
	v_mul_f32_e32 v111, v86, v120
	v_fmac_f32_e32 v111, v82, v124
	v_fmac_f32_e32 v111, v90, v162
	v_add_f32_e32 v111, v94, v111
	v_mul_f32_e32 v113, 0xbfb8aa3b, v111
	v_mul_f32_e32 v115, 0xbfb8aa3b, v114
	v_exp_f32_e32 v113, v113
	v_exp_f32_e32 v115, v115
	ds_read_b128 v[168:171], v104 offset:544
	s_waitcnt lgkmcnt(1)
	v_mul_f32_e32 v118, v72, v164
	v_add_f32_e32 v113, 1.0, v113
	v_add_f32_e32 v115, 1.0, v115
	v_rcp_f32_e32 v113, v113
	v_rcp_f32_e32 v115, v115
	v_fmac_f32_e32 v118, v64, v156
	s_waitcnt lgkmcnt(0)
	v_fmac_f32_e32 v118, v68, v168
	v_add_f32_e32 v118, v76, v118
	v_mul_f32_e32 v119, 0xbfb8aa3b, v118
	v_exp_f32_e32 v119, v119
	v_mul_f32_e32 v111, v111, v113
	v_mul_f32_e32 v113, v114, v115
	v_mul_f32_e32 v115, v73, v165
	v_fmac_f32_e32 v115, v65, v157
	v_fmac_f32_e32 v115, v69, v169
	v_add_f32_e32 v115, v77, v115
	v_add_f32_e32 v114, 1.0, v119
	v_mul_f32_e32 v119, 0xbfb8aa3b, v115
	v_rcp_f32_e32 v114, v114
	v_exp_f32_e32 v119, v119
	v_mul_f32_e32 v121, v75, v167
	v_fmac_f32_e32 v121, v67, v159
	v_mul_f32_e32 v114, v118, v114
	v_add_f32_e32 v118, 1.0, v119
	v_mul_f32_e32 v119, v74, v166
	v_fmac_f32_e32 v119, v66, v158
	v_fmac_f32_e32 v119, v70, v170
	v_add_f32_e32 v119, v78, v119
	v_fmac_f32_e32 v121, v71, v171
	v_mul_f32_e32 v120, 0xbfb8aa3b, v119
	v_add_f32_e32 v121, v79, v121
	v_rcp_f32_e32 v118, v118
	v_exp_f32_e32 v120, v120
	v_mul_f32_e32 v122, 0xbfb8aa3b, v121
	v_exp_f32_e32 v122, v122
	ds_read_b128 v[172:175], v104 offset:256
	ds_read_b128 v[176:179], v104 offset:272
	v_mul_f32_e32 v115, v115, v118
	v_add_f32_e32 v118, 1.0, v120
	v_rcp_f32_e32 v118, v118
	v_add_f32_e32 v120, 1.0, v122
	v_rcp_f32_e32 v120, v120
	s_waitcnt lgkmcnt(0)
	v_mul_f32_e32 v114, v176, v114
	v_mul_f32_e32 v115, v177, v115
	v_mul_f32_e32 v118, v119, v118
	v_mul_f32_e32 v122, v178, v118
	v_mul_f32_e32 v118, v121, v120
	v_cvt_pk_bf16_f32 v120, v114, v115
	v_add_u32_e32 v103, v103, v116
	v_mov_b64_e32 v[114:115], s[52:53]
	v_mad_i64_i32 v[114:115], s[6:7], v103, s16, v[114:115]
	v_mul_f32_e32 v121, v179, v118
	v_lshl_add_u64 v[114:115], v[96:97], 1, v[114:115]
	v_mul_f32_e32 v105, v172, v105
	v_mul_f32_e32 v109, v173, v109
	v_mul_f32_e32 v111, v174, v111
	v_mul_f32_e32 v113, v175, v113
	v_cvt_pk_bf16_f32 v118, v105, v109
	v_cvt_pk_bf16_f32 v119, v111, v113
	v_cvt_pk_bf16_f32 v121, v122, v121
	global_store_dwordx4 v[114:115], v[118:121], off
.LBB0_1018:
	s_or_b64 exec, exec, s[4:5]
	v_or_b32_e32 v113, 32, v110
	v_mul_u32_u24_e32 v103, 0x210, v113
	v_add3_u32 v103, v106, v103, v112
	v_add_u32_e32 v105, v102, v113
	v_add_u32_e32 v109, 0xfffffdf0, v103
	v_cmp_lt_i32_e64 s[4:5], v105, v117
	s_and_saveexec_b64 s[6:7], s[4:5]
	s_cbranch_execz .LBB0_1020
	ds_read_b128 v[118:121], v103
	ds_read_b128 v[122:125], v109
	ds_read_b128 v[156:159], v109 offset:16
	ds_read_b128 v[160:163], v103 offset:528
	ds_read_b128 v[164:167], v103 offset:16
	s_waitcnt lgkmcnt(4)
	v_mul_f32_e32 v111, v84, v118
	v_mul_f32_e32 v115, v85, v119
	s_waitcnt lgkmcnt(3)
	v_fmac_f32_e32 v111, v80, v122
	v_fmac_f32_e32 v115, v81, v123
	s_waitcnt lgkmcnt(1)
	v_fmac_f32_e32 v111, v88, v160
	v_fmac_f32_e32 v115, v89, v161
	v_add_f32_e32 v111, v92, v111
	v_add_f32_e32 v115, v93, v115
	v_mul_f32_e32 v114, 0xbfb8aa3b, v111
	v_mul_f32_e32 v118, 0xbfb8aa3b, v115
	v_exp_f32_e32 v114, v114
	v_exp_f32_e32 v118, v118
	v_mul_f32_e32 v119, v87, v121
	v_fmac_f32_e32 v119, v83, v125
	v_add_f32_e32 v114, 1.0, v114
	v_add_f32_e32 v118, 1.0, v118
	v_rcp_f32_e32 v114, v114
	v_rcp_f32_e32 v118, v118
	ds_read_b128 v[168:171], v103 offset:544
	v_fmac_f32_e32 v119, v91, v163
	v_mul_f32_e32 v111, v111, v114
	v_mul_f32_e32 v114, v115, v118
	v_mul_f32_e32 v115, v86, v120
	v_fmac_f32_e32 v115, v82, v124
	v_fmac_f32_e32 v115, v90, v162
	v_add_f32_e32 v115, v94, v115
	v_add_f32_e32 v119, v95, v119
	v_mul_f32_e32 v118, 0xbfb8aa3b, v115
	v_mul_f32_e32 v120, 0xbfb8aa3b, v119
	v_exp_f32_e32 v118, v118
	v_exp_f32_e32 v120, v120
	s_waitcnt lgkmcnt(1)
	v_mul_f32_e32 v121, v72, v164
	v_fmac_f32_e32 v121, v64, v156
	s_waitcnt lgkmcnt(0)
	v_fmac_f32_e32 v121, v68, v168
	v_add_f32_e32 v121, v76, v121
	v_add_f32_e32 v118, 1.0, v118
	v_add_f32_e32 v120, 1.0, v120
	v_mul_f32_e32 v122, 0xbfb8aa3b, v121
	v_rcp_f32_e32 v118, v118
	v_rcp_f32_e32 v120, v120
	v_exp_f32_e32 v122, v122
	ds_read_b128 v[172:175], v103 offset:256
	ds_read_b128 v[176:179], v103 offset:272
	v_mul_f32_e32 v115, v115, v118
	v_mul_f32_e32 v118, v119, v120
	v_add_f32_e32 v119, 1.0, v122
	v_mul_f32_e32 v120, v73, v165
	v_rcp_f32_e32 v119, v119
	v_fmac_f32_e32 v120, v65, v157
	v_fmac_f32_e32 v120, v69, v169
	v_add_f32_e32 v120, v77, v120
	v_mul_f32_e32 v122, 0xbfb8aa3b, v120
	v_exp_f32_e32 v122, v122
	s_waitcnt lgkmcnt(1)
	v_mul_f32_e32 v123, v175, v118
	v_mul_f32_e32 v118, v121, v119
	v_mul_f32_e32 v119, v74, v166
	v_fmac_f32_e32 v119, v66, v158
	v_mul_f32_e32 v124, v75, v167
	v_fmac_f32_e32 v119, v70, v170
	v_fmac_f32_e32 v124, v67, v159
	v_add_f32_e32 v119, v78, v119
	v_fmac_f32_e32 v124, v71, v171
	s_waitcnt lgkmcnt(0)
	v_mul_f32_e32 v121, v176, v118
	v_add_f32_e32 v118, 1.0, v122
	v_mul_f32_e32 v122, 0xbfb8aa3b, v119
	v_add_f32_e32 v124, v79, v124
	v_rcp_f32_e32 v118, v118
	v_exp_f32_e32 v122, v122
	v_mul_f32_e32 v125, 0xbfb8aa3b, v124
	v_exp_f32_e32 v125, v125
	v_mul_f32_e32 v118, v120, v118
	v_add_f32_e32 v120, 1.0, v122
	v_rcp_f32_e32 v120, v120
	v_add_f32_e32 v122, 1.0, v125
	v_rcp_f32_e32 v122, v122
	v_mul_f32_e32 v125, v177, v118
	v_mul_f32_e32 v118, v119, v120
	v_mul_f32_e32 v114, v173, v114
	v_mul_f32_e32 v115, v174, v115
	v_mul_f32_e32 v126, v178, v118
	v_mul_f32_e32 v118, v124, v122
	v_mul_f32_e32 v111, v172, v111
	v_mul_f32_e32 v122, v179, v118
	v_cvt_pk_bf16_f32 v118, v111, v114
	v_cvt_pk_bf16_f32 v119, v115, v123
	v_add_u32_e32 v105, v105, v116
	v_mov_b64_e32 v[114:115], s[52:53]
	v_mad_i64_i32 v[114:115], s[4:5], v105, s16, v[114:115]
	v_lshl_add_u64 v[114:115], v[96:97], 1, v[114:115]
	v_cvt_pk_bf16_f32 v120, v121, v125
	v_cvt_pk_bf16_f32 v121, v126, v122
	global_store_dwordx4 v[114:115], v[118:121], off
.LBB0_1020:
	s_or_b64 exec, exec, s[6:7]
	v_or_b32_e32 v114, 64, v110
	v_mul_u32_u24_e32 v105, 0x210, v114
	v_add3_u32 v105, v106, v105, v112
	v_add_u32_e32 v115, v102, v114
	v_add_u32_e32 v111, 0xfffffdf0, v105
	v_cmp_lt_i32_e64 s[4:5], v115, v117
	s_and_saveexec_b64 s[6:7], s[4:5]
	s_cbranch_execz .LBB0_1022
	ds_read_b128 v[118:121], v105
	ds_read_b128 v[122:125], v111
	ds_read_b128 v[156:159], v111 offset:16
	ds_read_b128 v[160:163], v105 offset:528
	ds_read_b128 v[164:167], v105 offset:16
	s_waitcnt lgkmcnt(4)
	v_mul_f32_e32 v119, v85, v119
	s_waitcnt lgkmcnt(3)
	v_fmac_f32_e32 v119, v81, v123
	v_mul_f32_e32 v118, v84, v118
	s_waitcnt lgkmcnt(1)
	v_fmac_f32_e32 v119, v89, v161
	v_add_f32_e32 v119, v93, v119
	v_mul_f32_e32 v123, 0xbfb8aa3b, v119
	v_fmac_f32_e32 v118, v80, v122
	v_exp_f32_e32 v123, v123
	v_fmac_f32_e32 v118, v88, v160
	v_add_f32_e32 v118, v92, v118
	v_mul_f32_e32 v122, 0xbfb8aa3b, v118
	v_exp_f32_e32 v122, v122
	v_add_f32_e32 v123, 1.0, v123
	v_rcp_f32_e32 v123, v123
	v_mul_f32_e32 v121, v87, v121
	v_fmac_f32_e32 v121, v83, v125
	v_fmac_f32_e32 v121, v91, v163
	v_add_f32_e32 v122, 1.0, v122
	v_add_f32_e32 v121, v95, v121
	v_rcp_f32_e32 v122, v122
	v_mul_f32_e32 v119, v119, v123
	v_mul_f32_e32 v120, v86, v120
	v_mul_f32_e32 v123, 0xbfb8aa3b, v121
	v_fmac_f32_e32 v120, v82, v124
	v_exp_f32_e32 v123, v123
	ds_read_b128 v[168:171], v105 offset:544
	v_fmac_f32_e32 v120, v90, v162
	v_add_f32_e32 v120, v94, v120
	v_mul_f32_e32 v118, v118, v122
	v_mul_f32_e32 v122, 0xbfb8aa3b, v120
	v_exp_f32_e32 v122, v122
	v_add_f32_e32 v123, 1.0, v123
	s_waitcnt lgkmcnt(1)
	v_mul_f32_e32 v124, v72, v164
	v_rcp_f32_e32 v123, v123
	v_fmac_f32_e32 v124, v64, v156
	s_waitcnt lgkmcnt(0)
	v_fmac_f32_e32 v124, v68, v168
	v_add_f32_e32 v124, v76, v124
	v_add_f32_e32 v122, 1.0, v122
	v_mul_f32_e32 v125, 0xbfb8aa3b, v124
	v_rcp_f32_e32 v122, v122
	v_exp_f32_e32 v125, v125
	v_mul_f32_e32 v121, v121, v123
	v_mul_f32_e32 v123, v73, v165
	v_fmac_f32_e32 v123, v65, v157
	v_fmac_f32_e32 v123, v69, v169
	v_add_f32_e32 v123, v77, v123
	v_mul_f32_e32 v120, v120, v122
	v_add_f32_e32 v122, 1.0, v125
	v_mul_f32_e32 v125, 0xbfb8aa3b, v123
	v_rcp_f32_e32 v122, v122
	v_exp_f32_e32 v125, v125
	v_mul_f32_e32 v127, v75, v167
	v_fmac_f32_e32 v127, v67, v159
	v_mul_f32_e32 v122, v124, v122
	v_add_f32_e32 v124, 1.0, v125
	v_mul_f32_e32 v125, v74, v166
	v_fmac_f32_e32 v125, v66, v158
	v_fmac_f32_e32 v125, v70, v170
	v_fmac_f32_e32 v127, v71, v171
	v_add_f32_e32 v125, v78, v125
	v_add_f32_e32 v127, v79, v127
	v_mul_f32_e32 v126, 0xbfb8aa3b, v125
	v_mul_f32_e32 v155, 0xbfb8aa3b, v127
	v_rcp_f32_e32 v124, v124
	v_exp_f32_e32 v126, v126
	v_exp_f32_e32 v155, v155
	ds_read_b128 v[172:175], v105 offset:256
	ds_read_b128 v[176:179], v105 offset:272
	v_mul_f32_e32 v123, v123, v124
	v_add_f32_e32 v124, 1.0, v126
	v_add_f32_e32 v126, 1.0, v155
	v_rcp_f32_e32 v124, v124
	v_rcp_f32_e32 v126, v126
	s_waitcnt lgkmcnt(1)
	v_mul_f32_e32 v118, v172, v118
	v_mul_f32_e32 v119, v173, v119
	v_mul_f32_e32 v120, v174, v120
	s_waitcnt lgkmcnt(0)
	v_mul_f32_e32 v122, v176, v122
	v_mul_f32_e32 v123, v177, v123
	v_mul_f32_e32 v121, v175, v121
	v_cvt_pk_bf16_f32 v118, v118, v119
	v_cvt_pk_bf16_f32 v119, v120, v121
	v_cvt_pk_bf16_f32 v120, v122, v123
	v_add_u32_e32 v115, v115, v116
	v_mov_b64_e32 v[122:123], s[52:53]
	v_mad_i64_i32 v[122:123], s[4:5], v115, s16, v[122:123]
	v_mul_f32_e32 v124, v125, v124
	v_mul_f32_e32 v125, v127, v126
	v_lshl_add_u64 v[122:123], v[96:97], 1, v[122:123]
	v_mul_f32_e32 v124, v178, v124
	v_mul_f32_e32 v125, v179, v125
	v_cvt_pk_bf16_f32 v121, v124, v125
	global_store_dwordx4 v[122:123], v[118:121], off
.LBB0_1022:
	s_or_b64 exec, exec, s[6:7]
	v_or_b32_e32 v115, 0x60, v110
	v_mul_u32_u24_e32 v118, 0x210, v115
	v_add_u32_e32 v102, v102, v115
	v_cmp_ne_u32_e64 s[4:5], 31, v110
	v_add3_u32 v106, v106, v118, v112
	v_cmp_lt_i32_e64 s[6:7], v102, v117
	v_add_u32_e32 v112, 0xfffffdf0, v106
	s_and_b64 s[24:25], s[4:5], s[6:7]
	s_and_saveexec_b64 s[6:7], s[24:25]
	s_cbranch_execz .LBB0_1024
	ds_read_b128 v[118:121], v106
	ds_read_b128 v[122:125], v112
	ds_read_b128 v[156:159], v112 offset:16
	ds_read_b128 v[160:163], v106 offset:528
	ds_read_b128 v[164:167], v106 offset:16
	ds_read_b128 v[168:171], v106 offset:544
	s_waitcnt lgkmcnt(5)
	v_mul_f32_e32 v84, v84, v118
	v_mul_f32_e32 v85, v85, v119
	s_waitcnt lgkmcnt(4)
	v_fmac_f32_e32 v84, v80, v122
	s_waitcnt lgkmcnt(1)
	v_mul_f32_e32 v72, v72, v164
	v_fmac_f32_e32 v72, v64, v156
	s_waitcnt lgkmcnt(0)
	v_fmac_f32_e32 v72, v68, v168
	v_add_f32_e32 v64, v76, v72
	v_mul_f32_e32 v68, 0xbfb8aa3b, v64
	v_exp_f32_e32 v68, v68
	v_fmac_f32_e32 v85, v81, v123
	v_mul_f32_e32 v73, v73, v165
	v_fmac_f32_e32 v84, v88, v160
	v_fmac_f32_e32 v85, v89, v161
	v_fmac_f32_e32 v73, v65, v157
	v_add_f32_e32 v80, v92, v84
	v_add_f32_e32 v81, v93, v85
	v_fmac_f32_e32 v73, v69, v169
	v_mul_f32_e32 v84, 0xbfb8aa3b, v80
	v_mul_f32_e32 v85, 0xbfb8aa3b, v81
	v_add_f32_e32 v68, 1.0, v68
	v_add_f32_e32 v65, v77, v73
	v_exp_f32_e32 v84, v84
	v_exp_f32_e32 v85, v85
	ds_read_b128 v[172:175], v106 offset:256
	ds_read_b128 v[176:179], v106 offset:272
	v_rcp_f32_e32 v68, v68
	v_mul_f32_e32 v69, 0xbfb8aa3b, v65
	v_exp_f32_e32 v69, v69
	v_add_f32_e32 v84, 1.0, v84
	v_add_f32_e32 v85, 1.0, v85
	v_mul_f32_e32 v64, v64, v68
	v_rcp_f32_e32 v84, v84
	v_rcp_f32_e32 v85, v85
	s_waitcnt lgkmcnt(0)
	v_mul_f32_e32 v68, v176, v64
	v_add_f32_e32 v64, 1.0, v69
	v_mul_f32_e32 v69, v74, v166
	v_fmac_f32_e32 v69, v66, v158
	v_fmac_f32_e32 v69, v70, v170
	v_mul_f32_e32 v70, v75, v167
	v_fmac_f32_e32 v70, v67, v159
	v_mul_f32_e32 v80, v80, v84
	v_mul_f32_e32 v81, v81, v85
	v_mul_f32_e32 v84, v86, v120
	v_mul_f32_e32 v85, v87, v121
	v_add_f32_e32 v66, v78, v69
	v_fmac_f32_e32 v70, v71, v171
	v_fmac_f32_e32 v84, v82, v124
	v_fmac_f32_e32 v85, v83, v125
	v_mul_f32_e32 v69, 0xbfb8aa3b, v66
	v_add_f32_e32 v67, v79, v70
	v_fmac_f32_e32 v84, v90, v162
	v_fmac_f32_e32 v85, v91, v163
	v_rcp_f32_e32 v64, v64
	v_exp_f32_e32 v69, v69
	v_mul_f32_e32 v70, 0xbfb8aa3b, v67
	v_add_f32_e32 v82, v94, v84
	v_add_f32_e32 v83, v95, v85
	v_exp_f32_e32 v70, v70
	v_mul_f32_e32 v84, 0xbfb8aa3b, v82
	v_mul_f32_e32 v85, 0xbfb8aa3b, v83
	v_exp_f32_e32 v84, v84
	v_exp_f32_e32 v85, v85
	v_mul_f32_e32 v64, v65, v64
	v_add_f32_e32 v65, 1.0, v69
	v_rcp_f32_e32 v65, v65
	v_add_f32_e32 v69, 1.0, v70
	v_rcp_f32_e32 v69, v69
	v_add_f32_e32 v84, 1.0, v84
	v_add_f32_e32 v85, 1.0, v85
	v_rcp_f32_e32 v84, v84
	v_rcp_f32_e32 v85, v85
	v_mul_f32_e32 v70, v177, v64
	v_mul_f32_e32 v64, v66, v65
	v_mul_f32_e32 v71, v178, v64
	v_mul_f32_e32 v64, v67, v69
	v_cvt_pk_bf16_f32 v66, v68, v70
	v_add_u32_e32 v70, v102, v116
	v_mov_b64_e32 v[68:69], s[52:53]
	v_mad_i64_i32 v[68:69], s[24:25], v70, s16, v[68:69]
	v_mul_f32_e32 v72, v82, v84
	v_mul_f32_e32 v76, v83, v85
	v_mul_f32_e32 v67, v179, v64
	v_lshl_add_u64 v[68:69], v[96:97], 1, v[68:69]
	v_mul_f32_e32 v80, v172, v80
	v_mul_f32_e32 v81, v173, v81
	v_mul_f32_e32 v72, v174, v72
	v_mul_f32_e32 v73, v175, v76
	v_cvt_pk_bf16_f32 v64, v80, v81
	v_cvt_pk_bf16_f32 v65, v72, v73
	v_cvt_pk_bf16_f32 v67, v71, v67
	global_store_dwordx4 v[68:69], v[64:67], off
.LBB0_1024:
	s_or_b64 exec, exec, s[6:7]
	s_barrier
	ds_write_b128 v134, v[60:63]
	ds_write_b128 v134, v[56:59] offset:64
	ds_write_b128 v134, v[48:51] offset:8448
	ds_write_b128 v134, v[44:47] offset:8512
	ds_write_b128 v134, v[40:43] offset:16896
	ds_write_b128 v134, v[36:39] offset:16960
	ds_write_b128 v134, v[32:35] offset:25344
	ds_write_b128 v134, v[28:31] offset:25408
	ds_write_b128 v134, v[24:27] offset:33792
	ds_write_b128 v134, v[20:23] offset:33856
	ds_write_b128 v134, v[16:19] offset:42240
	ds_write_b128 v134, v[12:15] offset:42304
	ds_write_b128 v134, v[8:11] offset:50688
	ds_write_b128 v134, v[4:7] offset:50752
	ds_write_b128 v134, v[0:3] offset:59136
	ds_write_b128 v134, v[52:55] offset:59200
	s_waitcnt lgkmcnt(0)
	s_barrier
	s_and_saveexec_b64 s[6:7], vcc
	s_xor_b64 s[6:7], exec, s[6:7]
	v_add_u32_e32 v0, 0xffffff78, v107
	v_mul_hi_u32 v1, v0, s12
	v_lshrrev_b32_e32 v1, 1, v1
	v_lshl_add_u32 v34, v1, 8, v149
	v_lshl_add_u32 v1, v1, 1, v1
	v_sub_u32_e32 v32, v0, v1
	s_or_saveexec_b64 s[6:7], s[6:7]
	v_mov_b32_e32 v35, 0x100
	s_xor_b64 exec, exec, s[6:7]
	v_mul_hi_i32 v0, v107, s14
	v_lshrrev_b32_e32 v1, 31, v0
	v_ashrrev_i32_e32 v0, 3, v0
	v_add_u32_e32 v0, v0, v1
	v_lshlrev_b32_e32 v34, 11, v0
	v_lshl_add_u32 v0, v0, 4, v0
	v_sub_u32_e32 v32, v107, v0
	v_mov_b32_e32 v35, 0x800
	s_or_b64 exec, exec, s[6:7]
	v_or_b32_e32 v4, 64, v96
	v_ashrrev_i32_e32 v5, 31, v4
	v_lshlrev_b64 v[4:5], 2, v[4:5]
	v_lshl_add_u64 v[6:7], s[8:9], 0, v[4:5]
	v_lshl_add_u64 v[4:5], s[10:11], 0, v[4:5]
	s_waitcnt vmcnt(0)
	v_mov_b64_e32 v[16:17], v[200:201]
	v_mov_b64_e32 v[18:19], v[202:203]
	v_mov_b64_e32 v[0:1], v[204:205]
	v_mov_b64_e32 v[2:3], v[206:207]
	v_mov_b64_e32 v[20:21], v[208:209]
	v_mov_b64_e32 v[22:23], v[210:211]
	v_mov_b64_e32 v[8:9], v[212:213]
	v_mov_b64_e32 v[10:11], v[214:215]
	v_mov_b64_e32 v[24:25], v[216:217]
	v_mov_b64_e32 v[26:27], v[218:219]
	s_nop 0
	v_mov_b64_e32 v[4:5], v[220:221]
	v_mov_b64_e32 v[6:7], v[222:223]
	s_nop 0
	v_mov_b64_e32 v[28:29], v[224:225]
	v_mov_b64_e32 v[30:31], v[226:227]
	v_mov_b64_e32 v[12:13], v[228:229]
	v_mov_b64_e32 v[14:15], v[230:231]
	v_mad_u64_u32 v[32:33], s[6:7], v32, s15, -1
	v_add_u32_e32 v33, v32, v110
	v_cmp_lt_i32_e32 vcc, v33, v35
	s_and_b64 s[6:7], s[0:1], vcc
	s_and_saveexec_b64 s[0:1], s[6:7]
	s_cbranch_execz .LBB0_1030
	ds_read_b128 v[36:39], v104
	ds_read_b128 v[40:43], v108
	ds_read_b128 v[44:47], v108 offset:16
	ds_read_b128 v[48:51], v104 offset:528
	ds_read_b128 v[52:55], v104 offset:16
	s_waitcnt lgkmcnt(4)
	v_mul_f32_e32 v37, v21, v37
	s_waitcnt lgkmcnt(3)
	v_fmac_f32_e32 v37, v17, v41
	v_mul_f32_e32 v36, v20, v36
	s_waitcnt lgkmcnt(1)
	v_fmac_f32_e32 v37, v25, v49
	v_add_f32_e32 v37, v29, v37
	v_mul_f32_e32 v41, 0xbfb8aa3b, v37
	v_fmac_f32_e32 v36, v16, v40
	v_exp_f32_e32 v41, v41
	v_fmac_f32_e32 v36, v24, v48
	v_add_f32_e32 v36, v28, v36
	v_mul_f32_e32 v40, 0xbfb8aa3b, v36
	v_exp_f32_e32 v40, v40
	v_add_f32_e32 v41, 1.0, v41
	v_rcp_f32_e32 v41, v41
	v_mul_f32_e32 v39, v23, v39
	v_fmac_f32_e32 v39, v19, v43
	v_fmac_f32_e32 v39, v27, v51
	v_add_f32_e32 v40, 1.0, v40
	v_add_f32_e32 v39, v31, v39
	v_rcp_f32_e32 v40, v40
	v_mul_f32_e32 v37, v37, v41
	v_mul_f32_e32 v38, v22, v38
	v_mul_f32_e32 v41, 0xbfb8aa3b, v39
	v_fmac_f32_e32 v38, v18, v42
	v_exp_f32_e32 v41, v41
	ds_read_b128 v[56:59], v104 offset:544
	v_fmac_f32_e32 v38, v26, v50
	v_add_f32_e32 v38, v30, v38
	v_mul_f32_e32 v36, v36, v40
	v_mul_f32_e32 v40, 0xbfb8aa3b, v38
	v_exp_f32_e32 v40, v40
	v_add_f32_e32 v41, 1.0, v41
	s_waitcnt lgkmcnt(1)
	v_mul_f32_e32 v42, v8, v52
	v_rcp_f32_e32 v41, v41
	v_fmac_f32_e32 v42, v0, v44
	s_waitcnt lgkmcnt(0)
	v_fmac_f32_e32 v42, v4, v56
	v_add_f32_e32 v42, v12, v42
	v_add_f32_e32 v40, 1.0, v40
	v_mul_f32_e32 v43, 0xbfb8aa3b, v42
	v_rcp_f32_e32 v40, v40
	v_exp_f32_e32 v43, v43
	v_mul_f32_e32 v39, v39, v41
	v_mul_f32_e32 v41, v9, v53
	v_fmac_f32_e32 v41, v1, v45
	v_fmac_f32_e32 v41, v5, v57
	v_add_f32_e32 v41, v13, v41
	v_mul_f32_e32 v38, v38, v40
	v_add_f32_e32 v40, 1.0, v43
	v_mul_f32_e32 v43, 0xbfb8aa3b, v41
	v_rcp_f32_e32 v40, v40
	v_exp_f32_e32 v43, v43
	v_mul_f32_e32 v45, v11, v55
	v_fmac_f32_e32 v45, v3, v47
	v_mul_f32_e32 v40, v42, v40
	v_add_f32_e32 v42, 1.0, v43
	v_mul_f32_e32 v43, v10, v54
	v_fmac_f32_e32 v43, v2, v46
	v_fmac_f32_e32 v43, v6, v58
	v_fmac_f32_e32 v45, v7, v59
	v_add_f32_e32 v43, v14, v43
	v_add_f32_e32 v45, v15, v45
	v_mul_f32_e32 v44, 0xbfb8aa3b, v43
	v_mul_f32_e32 v46, 0xbfb8aa3b, v45
	v_rcp_f32_e32 v42, v42
	v_exp_f32_e32 v44, v44
	v_exp_f32_e32 v46, v46
	ds_read_b128 v[60:63], v104 offset:256
	ds_read_b128 v[64:67], v104 offset:272
	v_mul_f32_e32 v41, v41, v42
	v_add_f32_e32 v42, 1.0, v44
	v_add_f32_e32 v44, 1.0, v46
	v_rcp_f32_e32 v42, v42
	v_rcp_f32_e32 v44, v44
	s_waitcnt lgkmcnt(1)
	v_mul_f32_e32 v36, v60, v36
	v_mul_f32_e32 v37, v61, v37
	v_mul_f32_e32 v38, v62, v38
	s_waitcnt lgkmcnt(0)
	v_mul_f32_e32 v40, v64, v40
	v_mul_f32_e32 v41, v65, v41
	v_mul_f32_e32 v39, v63, v39
	v_cvt_pk_bf16_f32 v36, v36, v37
	v_cvt_pk_bf16_f32 v37, v38, v39
	v_cvt_pk_bf16_f32 v38, v40, v41
	v_add_u32_e32 v33, v33, v34
	v_mov_b64_e32 v[40:41], s[52:53]
	v_mad_i64_i32 v[40:41], s[6:7], v33, s16, v[40:41]
	v_mul_f32_e32 v42, v43, v42
	v_mul_f32_e32 v43, v45, v44
	v_lshl_add_u64 v[40:41], v[96:97], 1, v[40:41]
	v_mul_f32_e32 v42, v66, v42
	v_mul_f32_e32 v43, v67, v43
	v_cvt_pk_bf16_f32 v39, v42, v43
	global_store_dwordx4 v[40:41], v[36:39], off offset:128
.LBB0_1030:
	s_or_b64 exec, exec, s[0:1]
	v_add_u32_e32 v33, v32, v113
	v_cmp_lt_i32_e32 vcc, v33, v35
	s_and_saveexec_b64 s[0:1], vcc
	s_cbranch_execz .LBB0_1032
	ds_read_b128 v[36:39], v103
	ds_read_b128 v[40:43], v109
	ds_read_b128 v[44:47], v109 offset:16
	ds_read_b128 v[48:51], v103 offset:528
	ds_read_b128 v[52:55], v103 offset:16
	s_waitcnt lgkmcnt(4)
	v_mul_f32_e32 v37, v21, v37
	s_waitcnt lgkmcnt(3)
	v_fmac_f32_e32 v37, v17, v41
	v_mul_f32_e32 v36, v20, v36
	s_waitcnt lgkmcnt(1)
	v_fmac_f32_e32 v37, v25, v49
	v_add_f32_e32 v37, v29, v37
	v_mul_f32_e32 v41, 0xbfb8aa3b, v37
	v_fmac_f32_e32 v36, v16, v40
	v_exp_f32_e32 v41, v41
	v_fmac_f32_e32 v36, v24, v48
	v_add_f32_e32 v36, v28, v36
	v_mul_f32_e32 v40, 0xbfb8aa3b, v36
	v_exp_f32_e32 v40, v40
	v_add_f32_e32 v41, 1.0, v41
	v_rcp_f32_e32 v41, v41
	v_mul_f32_e32 v39, v23, v39
	v_fmac_f32_e32 v39, v19, v43
	v_fmac_f32_e32 v39, v27, v51
	v_add_f32_e32 v40, 1.0, v40
	v_add_f32_e32 v39, v31, v39
	v_rcp_f32_e32 v40, v40
	v_mul_f32_e32 v37, v37, v41
	v_mul_f32_e32 v38, v22, v38
	v_mul_f32_e32 v41, 0xbfb8aa3b, v39
	v_fmac_f32_e32 v38, v18, v42
	v_exp_f32_e32 v41, v41
	ds_read_b128 v[56:59], v103 offset:544
	v_fmac_f32_e32 v38, v26, v50
	v_add_f32_e32 v38, v30, v38
	v_mul_f32_e32 v36, v36, v40
	v_mul_f32_e32 v40, 0xbfb8aa3b, v38
	v_exp_f32_e32 v40, v40
	v_add_f32_e32 v41, 1.0, v41
	s_waitcnt lgkmcnt(1)
	v_mul_f32_e32 v42, v8, v52
	v_rcp_f32_e32 v41, v41
	v_fmac_f32_e32 v42, v0, v44
	s_waitcnt lgkmcnt(0)
	v_fmac_f32_e32 v42, v4, v56
	v_add_f32_e32 v42, v12, v42
	v_add_f32_e32 v40, 1.0, v40
	v_mul_f32_e32 v43, 0xbfb8aa3b, v42
	v_rcp_f32_e32 v40, v40
	v_exp_f32_e32 v43, v43
	v_mul_f32_e32 v39, v39, v41
	v_mul_f32_e32 v41, v9, v53
	v_fmac_f32_e32 v41, v1, v45
	v_fmac_f32_e32 v41, v5, v57
	v_add_f32_e32 v41, v13, v41
	v_mul_f32_e32 v38, v38, v40
	v_add_f32_e32 v40, 1.0, v43
	v_mul_f32_e32 v43, 0xbfb8aa3b, v41
	v_rcp_f32_e32 v40, v40
	v_exp_f32_e32 v43, v43
	v_mul_f32_e32 v45, v11, v55
	v_fmac_f32_e32 v45, v3, v47
	v_mul_f32_e32 v40, v42, v40
	v_add_f32_e32 v42, 1.0, v43
	v_mul_f32_e32 v43, v10, v54
	v_fmac_f32_e32 v43, v2, v46
	v_fmac_f32_e32 v43, v6, v58
	v_fmac_f32_e32 v45, v7, v59
	v_add_f32_e32 v43, v14, v43
	v_add_f32_e32 v45, v15, v45
	v_mul_f32_e32 v44, 0xbfb8aa3b, v43
	v_mul_f32_e32 v46, 0xbfb8aa3b, v45
	v_rcp_f32_e32 v42, v42
	v_exp_f32_e32 v44, v44
	v_exp_f32_e32 v46, v46
	ds_read_b128 v[60:63], v103 offset:256
	ds_read_b128 v[64:67], v103 offset:272
	v_mul_f32_e32 v41, v41, v42
	v_add_f32_e32 v42, 1.0, v44
	v_add_f32_e32 v44, 1.0, v46
	v_rcp_f32_e32 v42, v42
	v_rcp_f32_e32 v44, v44
	s_waitcnt lgkmcnt(1)
	v_mul_f32_e32 v36, v60, v36
	v_mul_f32_e32 v37, v61, v37
	v_mul_f32_e32 v38, v62, v38
	s_waitcnt lgkmcnt(0)
	v_mul_f32_e32 v40, v64, v40
	v_mul_f32_e32 v41, v65, v41
	v_mul_f32_e32 v39, v63, v39
	v_cvt_pk_bf16_f32 v36, v36, v37
	v_cvt_pk_bf16_f32 v37, v38, v39
	v_cvt_pk_bf16_f32 v38, v40, v41
	v_add_u32_e32 v33, v33, v34
	v_mov_b64_e32 v[40:41], s[52:53]
	v_mad_i64_i32 v[40:41], s[6:7], v33, s16, v[40:41]
	v_mul_f32_e32 v42, v43, v42
	v_mul_f32_e32 v43, v45, v44
	v_lshl_add_u64 v[40:41], v[96:97], 1, v[40:41]
	v_mul_f32_e32 v42, v66, v42
	v_mul_f32_e32 v43, v67, v43
	v_cvt_pk_bf16_f32 v39, v42, v43
	global_store_dwordx4 v[40:41], v[36:39], off offset:128
.LBB0_1032:
	s_or_b64 exec, exec, s[0:1]
	v_add_u32_e32 v33, v32, v114
	v_cmp_lt_i32_e32 vcc, v33, v35
	s_and_saveexec_b64 s[0:1], vcc
	s_cbranch_execz .LBB0_1034
	ds_read_b128 v[36:39], v105
	ds_read_b128 v[40:43], v111
	ds_read_b128 v[44:47], v111 offset:16
	ds_read_b128 v[48:51], v105 offset:528
	ds_read_b128 v[52:55], v105 offset:16
	s_waitcnt lgkmcnt(4)
	v_mul_f32_e32 v37, v21, v37
	s_waitcnt lgkmcnt(3)
	v_fmac_f32_e32 v37, v17, v41
	v_mul_f32_e32 v36, v20, v36
	s_waitcnt lgkmcnt(1)
	v_fmac_f32_e32 v37, v25, v49
	v_add_f32_e32 v37, v29, v37
	v_mul_f32_e32 v41, 0xbfb8aa3b, v37
	v_fmac_f32_e32 v36, v16, v40
	v_exp_f32_e32 v41, v41
	v_fmac_f32_e32 v36, v24, v48
	v_add_f32_e32 v36, v28, v36
	v_mul_f32_e32 v40, 0xbfb8aa3b, v36
	v_exp_f32_e32 v40, v40
	v_add_f32_e32 v41, 1.0, v41
	v_rcp_f32_e32 v41, v41
	v_mul_f32_e32 v39, v23, v39
	v_fmac_f32_e32 v39, v19, v43
	v_fmac_f32_e32 v39, v27, v51
	v_add_f32_e32 v40, 1.0, v40
	v_add_f32_e32 v39, v31, v39
	v_rcp_f32_e32 v40, v40
	v_mul_f32_e32 v37, v37, v41
	v_mul_f32_e32 v38, v22, v38
	v_mul_f32_e32 v41, 0xbfb8aa3b, v39
	v_fmac_f32_e32 v38, v18, v42
	v_exp_f32_e32 v41, v41
	ds_read_b128 v[56:59], v105 offset:544
	v_fmac_f32_e32 v38, v26, v50
	v_add_f32_e32 v38, v30, v38
	v_mul_f32_e32 v36, v36, v40
	v_mul_f32_e32 v40, 0xbfb8aa3b, v38
	v_exp_f32_e32 v40, v40
	v_add_f32_e32 v41, 1.0, v41
	s_waitcnt lgkmcnt(1)
	v_mul_f32_e32 v42, v8, v52
	v_rcp_f32_e32 v41, v41
	v_fmac_f32_e32 v42, v0, v44
	s_waitcnt lgkmcnt(0)
	v_fmac_f32_e32 v42, v4, v56
	v_add_f32_e32 v42, v12, v42
	v_add_f32_e32 v40, 1.0, v40
	v_mul_f32_e32 v43, 0xbfb8aa3b, v42
	v_rcp_f32_e32 v40, v40
	v_exp_f32_e32 v43, v43
	v_mul_f32_e32 v39, v39, v41
	v_mul_f32_e32 v41, v9, v53
	v_fmac_f32_e32 v41, v1, v45
	v_fmac_f32_e32 v41, v5, v57
	v_add_f32_e32 v41, v13, v41
	v_mul_f32_e32 v38, v38, v40
	v_add_f32_e32 v40, 1.0, v43
	v_mul_f32_e32 v43, 0xbfb8aa3b, v41
	v_rcp_f32_e32 v40, v40
	v_exp_f32_e32 v43, v43
	v_mul_f32_e32 v45, v11, v55
	v_fmac_f32_e32 v45, v3, v47
	v_mul_f32_e32 v40, v42, v40
	v_add_f32_e32 v42, 1.0, v43
	v_mul_f32_e32 v43, v10, v54
	v_fmac_f32_e32 v43, v2, v46
	v_fmac_f32_e32 v43, v6, v58
	v_fmac_f32_e32 v45, v7, v59
	v_add_f32_e32 v43, v14, v43
	v_add_f32_e32 v45, v15, v45
	v_mul_f32_e32 v44, 0xbfb8aa3b, v43
	v_mul_f32_e32 v46, 0xbfb8aa3b, v45
	v_rcp_f32_e32 v42, v42
	v_exp_f32_e32 v44, v44
	v_exp_f32_e32 v46, v46
	ds_read_b128 v[60:63], v105 offset:256
	ds_read_b128 v[64:67], v105 offset:272
	v_mul_f32_e32 v41, v41, v42
	v_add_f32_e32 v42, 1.0, v44
	v_add_f32_e32 v44, 1.0, v46
	v_rcp_f32_e32 v42, v42
	v_rcp_f32_e32 v44, v44
	s_waitcnt lgkmcnt(1)
	v_mul_f32_e32 v36, v60, v36
	v_mul_f32_e32 v37, v61, v37
	v_mul_f32_e32 v38, v62, v38
	s_waitcnt lgkmcnt(0)
	v_mul_f32_e32 v40, v64, v40
	v_mul_f32_e32 v41, v65, v41
	v_mul_f32_e32 v39, v63, v39
	v_cvt_pk_bf16_f32 v36, v36, v37
	v_cvt_pk_bf16_f32 v37, v38, v39
	v_cvt_pk_bf16_f32 v38, v40, v41
	v_add_u32_e32 v33, v33, v34
	v_mov_b64_e32 v[40:41], s[52:53]
	v_mad_i64_i32 v[40:41], s[6:7], v33, s16, v[40:41]
	v_mul_f32_e32 v42, v43, v42
	v_mul_f32_e32 v43, v45, v44
	v_lshl_add_u64 v[40:41], v[96:97], 1, v[40:41]
	v_mul_f32_e32 v42, v66, v42
	v_mul_f32_e32 v43, v67, v43
	v_cvt_pk_bf16_f32 v39, v42, v43
	global_store_dwordx4 v[40:41], v[36:39], off offset:128
.LBB0_1034:
	s_or_b64 exec, exec, s[0:1]
	v_add_u32_e32 v32, v32, v115
	v_cmp_lt_i32_e32 vcc, v32, v35
	s_and_b64 s[4:5], s[4:5], vcc
	s_and_saveexec_b64 s[0:1], s[4:5]
	s_cbranch_execz .LBB0_991
	ds_read_b128 v[36:39], v106
	ds_read_b128 v[40:43], v112
	ds_read_b128 v[44:47], v112 offset:16
	ds_read_b128 v[48:51], v106 offset:528
	ds_read_b128 v[52:55], v106 offset:16
	ds_read_b128 v[56:59], v106 offset:544
	s_waitcnt lgkmcnt(5)
	v_mul_f32_e32 v20, v20, v36
	v_mul_f32_e32 v21, v21, v37
	s_waitcnt lgkmcnt(4)
	v_fmac_f32_e32 v20, v16, v40
	s_waitcnt lgkmcnt(1)
	v_mul_f32_e32 v8, v8, v52
	v_fmac_f32_e32 v8, v0, v44
	s_waitcnt lgkmcnt(0)
	v_fmac_f32_e32 v8, v4, v56
	v_add_f32_e32 v0, v12, v8
	v_mul_f32_e32 v4, 0xbfb8aa3b, v0
	v_exp_f32_e32 v4, v4
	v_fmac_f32_e32 v21, v17, v41
	v_mul_f32_e32 v9, v9, v53
	v_fmac_f32_e32 v20, v24, v48
	v_fmac_f32_e32 v21, v25, v49
	v_fmac_f32_e32 v9, v1, v45
	v_add_f32_e32 v16, v28, v20
	v_add_f32_e32 v17, v29, v21
	v_fmac_f32_e32 v9, v5, v57
	v_mul_f32_e32 v20, 0xbfb8aa3b, v16
	v_mul_f32_e32 v21, 0xbfb8aa3b, v17
	v_add_f32_e32 v4, 1.0, v4
	v_add_f32_e32 v1, v13, v9
	v_exp_f32_e32 v20, v20
	v_exp_f32_e32 v21, v21
	ds_read_b128 v[60:63], v106 offset:256
	ds_read_b128 v[64:67], v106 offset:272
	v_rcp_f32_e32 v4, v4
	v_mul_f32_e32 v5, 0xbfb8aa3b, v1
	v_exp_f32_e32 v5, v5
	v_add_f32_e32 v20, 1.0, v20
	v_add_f32_e32 v21, 1.0, v21
	v_mul_f32_e32 v0, v0, v4
	v_rcp_f32_e32 v20, v20
	v_rcp_f32_e32 v21, v21
	s_waitcnt lgkmcnt(0)
	v_mul_f32_e32 v4, v64, v0
	v_add_f32_e32 v0, 1.0, v5
	v_mul_f32_e32 v5, v10, v54
	v_fmac_f32_e32 v5, v2, v46
	v_fmac_f32_e32 v5, v6, v58
	v_mul_f32_e32 v6, v11, v55
	v_fmac_f32_e32 v6, v3, v47
	v_mul_f32_e32 v16, v16, v20
	v_mul_f32_e32 v17, v17, v21
	v_mul_f32_e32 v20, v22, v38
	v_mul_f32_e32 v21, v23, v39
	v_add_f32_e32 v2, v14, v5
	v_fmac_f32_e32 v6, v7, v59
	v_fmac_f32_e32 v20, v18, v42
	v_fmac_f32_e32 v21, v19, v43
	v_mul_f32_e32 v5, 0xbfb8aa3b, v2
	v_add_f32_e32 v3, v15, v6
	v_fmac_f32_e32 v20, v26, v50
	v_fmac_f32_e32 v21, v27, v51
	v_rcp_f32_e32 v0, v0
	v_exp_f32_e32 v5, v5
	v_mul_f32_e32 v6, 0xbfb8aa3b, v3
	v_add_f32_e32 v18, v30, v20
	v_add_f32_e32 v19, v31, v21
	v_exp_f32_e32 v6, v6
	v_mul_f32_e32 v20, 0xbfb8aa3b, v18
	v_mul_f32_e32 v21, 0xbfb8aa3b, v19
	v_exp_f32_e32 v20, v20
	v_exp_f32_e32 v21, v21
	v_mul_f32_e32 v0, v1, v0
	v_add_f32_e32 v1, 1.0, v5
	v_rcp_f32_e32 v1, v1
	v_add_f32_e32 v5, 1.0, v6
	v_rcp_f32_e32 v5, v5
	v_add_f32_e32 v20, 1.0, v20
	v_add_f32_e32 v21, 1.0, v21
	v_rcp_f32_e32 v20, v20
	v_rcp_f32_e32 v21, v21
	v_mul_f32_e32 v6, v65, v0
	v_mul_f32_e32 v0, v2, v1
	v_mul_f32_e32 v7, v66, v0
	v_mul_f32_e32 v0, v3, v5
	v_cvt_pk_bf16_f32 v2, v4, v6
	v_add_u32_e32 v6, v32, v34
	v_mov_b64_e32 v[4:5], s[52:53]
	v_mad_i64_i32 v[4:5], s[4:5], v6, s16, v[4:5]
	v_mul_f32_e32 v8, v18, v20
	v_mul_f32_e32 v12, v19, v21
	v_mul_f32_e32 v3, v67, v0
	v_lshl_add_u64 v[4:5], v[96:97], 1, v[4:5]
	v_mul_f32_e32 v16, v60, v16
	v_mul_f32_e32 v17, v61, v17
	v_mul_f32_e32 v8, v62, v8
	v_mul_f32_e32 v9, v63, v12
	v_cvt_pk_bf16_f32 v0, v16, v17
	v_cvt_pk_bf16_f32 v1, v8, v9
	v_cvt_pk_bf16_f32 v3, v7, v3
	global_store_dwordx4 v[4:5], v[0:3], off offset:128
	s_branch .LBB0_991

.LBB0_2003:
	v_mov_b32_e32 v160, v128
	s_nop 1
	v_lshlrev_b32_sdwa v240, v176, v160 dst_sel:DWORD dst_unused:UNUSED_PAD src0_sel:DWORD src1_sel:BYTE_0
	v_and_b32_e32 v240, 56, v240
	v_lshl_or_b32 v240, s20, 7, v240
	v_ashrrev_i32_e32 v241, 31, v240
	v_lshlrev_b64 v[240:241], 2, v[240:241]
	v_lshl_add_u64 v[232:233], s[8:9], 0, v[240:241]
	v_lshl_add_u64 v[234:235], s[12:13], 0, v[240:241]
	v_lshl_add_u64 v[236:237], s[14:15], 0, v[240:241]
	v_lshl_add_u64 v[238:239], s[10:11], 0, v[240:241]
	global_load_dwordx4 v[200:203], v[232:233], off
	global_load_dwordx4 v[204:207], v[232:233], off offset:16
	global_load_dwordx4 v[208:211], v[234:235], off
	global_load_dwordx4 v[212:215], v[234:235], off offset:16
	global_load_dwordx4 v[216:219], v[236:237], off
	global_load_dwordx4 v[220:223], v[236:237], off offset:16
	global_load_dwordx4 v[224:227], v[238:239], off
	global_load_dwordx4 v[228:231], v[238:239], off offset:16
	s_nop 0
	v_and_b32_e32 v132, 15, v160
	v_ashrrev_i32_e32 v161, 8, v160
	v_mul_u32_u24_e32 v132, 0x210, v132
	v_lshlrev_b32_e32 v162, 1, v160
	v_mad_i32_i24 v132, v161, s29, v132
	v_and_b32_e32 v162, 0x180, v162
	v_and_b32_e32 v163, 48, v160
	v_add3_u32 v132, v132, v162, v163
	ds_write_b128 v132, v[124:127]
	ds_write_b128 v132, v[120:123] offset:64
	ds_write_b128 v132, v[116:119] offset:8448
	ds_write_b128 v132, v[112:115] offset:8512
	ds_write_b128 v132, v[108:111] offset:16896
	ds_write_b128 v132, v[104:107] offset:16960
	ds_write_b128 v132, v[100:103] offset:25344
	ds_write_b128 v132, v[96:99] offset:25408
	ds_write_b128 v132, v[92:95] offset:33792
	ds_write_b128 v132, v[88:91] offset:33856
	ds_write_b128 v132, v[84:87] offset:42240
	ds_write_b128 v132, v[80:83] offset:42304
	ds_write_b128 v132, v[76:79] offset:50688
	ds_write_b128 v132, v[72:75] offset:50752
	ds_write_b128 v132, v[68:71] offset:59136
	ds_write_b128 v132, v[64:67] offset:59200
	v_add_u32_e32 v103, s21, v161
	v_cmp_lt_i32_e32 vcc, s17, v103
	s_waitcnt lgkmcnt(0)
	s_barrier
	s_and_saveexec_b64 s[0:1], vcc
	s_xor_b64 s[0:1], exec, s[0:1]
	v_add_u32_e32 v64, 0xffffff78, v103
	v_mul_hi_u32 v65, v64, s24
	v_lshrrev_b32_e32 v65, 1, v65
	v_lshl_add_u32 v112, v65, 8, v159
	v_lshl_add_u32 v65, v65, 1, v65
	v_sub_u32_e32 v98, v64, v65
	s_or_saveexec_b64 s[0:1], s[0:1]
	v_mov_b32_e32 v113, 0x100
	s_xor_b64 exec, exec, s[0:1]
	v_mul_hi_i32 v64, v103, s16
	v_lshrrev_b32_e32 v65, 31, v64
	v_ashrrev_i32_e32 v64, 3, v64
	v_add_u32_e32 v64, v64, v65
	v_lshlrev_b32_e32 v112, 11, v64
	v_lshl_add_u32 v64, v64, 4, v64
	v_sub_u32_e32 v98, v103, v64
	v_mov_b32_e32 v113, 0x800
	s_or_b64 exec, exec, s[0:1]
	v_lshlrev_b32_sdwa v64, v176, v160 dst_sel:DWORD dst_unused:UNUSED_PAD src0_sel:DWORD src1_sel:BYTE_0
	v_and_b32_e32 v99, 56, v64
	v_lshl_or_b32 v96, s20, 7, v99
	v_ashrrev_i32_e32 v97, 31, v96
	v_lshlrev_b64 v[76:77], 2, v[96:97]
	v_lshl_add_u64 v[64:65], s[8:9], 0, v[76:77]
	v_lshl_add_u64 v[68:69], s[12:13], 0, v[76:77]
	s_waitcnt vmcnt(0)
	v_mov_b64_e32 v[80:81], v[200:201]
	v_mov_b64_e32 v[82:83], v[202:203]
	s_nop 0
	v_mov_b64_e32 v[64:65], v[204:205]
	v_mov_b64_e32 v[66:67], v[206:207]
	s_nop 0
	v_mov_b64_e32 v[84:85], v[208:209]
	v_mov_b64_e32 v[86:87], v[210:211]
	v_mov_b64_e32 v[72:73], v[212:213]
	v_mov_b64_e32 v[74:75], v[214:215]
	v_lshl_add_u64 v[68:69], s[14:15], 0, v[76:77]
	v_lshl_add_u64 v[76:77], s[10:11], 0, v[76:77]
	v_mov_b64_e32 v[88:89], v[216:217]
	v_mov_b64_e32 v[90:91], v[218:219]
	s_nop 0
	v_mov_b64_e32 v[68:69], v[220:221]
	v_mov_b64_e32 v[70:71], v[222:223]
	s_nop 0
	v_mov_b64_e32 v[92:93], v[224:225]
	v_mov_b64_e32 v[94:95], v[226:227]
	s_nop 0
	v_mov_b64_e32 v[76:77], v[228:229]
	v_mov_b64_e32 v[78:79], v[230:231]
	global_load_dwordx4 v[200:203], v[232:233], off offset:256
	global_load_dwordx4 v[204:207], v[232:233], off offset:272
	global_load_dwordx4 v[208:211], v[234:235], off offset:256
	global_load_dwordx4 v[212:215], v[234:235], off offset:272
	global_load_dwordx4 v[216:219], v[236:237], off offset:256
	global_load_dwordx4 v[220:223], v[236:237], off offset:272
	global_load_dwordx4 v[224:227], v[238:239], off offset:256
	global_load_dwordx4 v[228:231], v[238:239], off offset:272
	v_bfe_u32 v106, v160, 3, 5
	v_lshlrev_b32_e32 v108, 2, v99
	v_mad_u64_u32 v[98:99], s[0:1], v98, s26, -1
	v_mul_i32_i24_e32 v102, 0x12000, v161
	v_mul_u32_u24_e32 v100, 0x210, v106
	v_add_u32_e32 v99, v98, v106
	v_cmp_gt_u32_sdwa s[20:21], v160, v177 src0_sel:BYTE_0 src1_sel:DWORD
	v_add3_u32 v100, v102, v100, v108
	v_cmp_lt_i32_e64 s[0:1], v99, v113
	v_add_u32_e32 v104, 0xfffffdf0, v100
	s_and_b64 s[6:7], s[20:21], s[0:1]
	s_and_saveexec_b64 s[0:1], s[6:7]
	s_cbranch_execz .LBB0_2009
	ds_read_b128 v[114:117], v100
	ds_read_b128 v[118:121], v104
	ds_read_b128 v[122:125], v104 offset:16
	ds_read_b128 v[160:163], v100 offset:528
	ds_read_b128 v[164:167], v100 offset:16
	s_waitcnt lgkmcnt(4)
	v_mul_f32_e32 v101, v84, v114
	v_mul_f32_e32 v107, v85, v115
	s_waitcnt lgkmcnt(3)
	v_fmac_f32_e32 v101, v80, v118
	v_fmac_f32_e32 v107, v81, v119
	s_waitcnt lgkmcnt(1)
	v_fmac_f32_e32 v101, v88, v160
	v_fmac_f32_e32 v107, v89, v161
	v_add_f32_e32 v101, v92, v101
	v_add_f32_e32 v107, v93, v107
	v_mul_f32_e32 v105, 0xbfb8aa3b, v101
	v_mul_f32_e32 v109, 0xbfb8aa3b, v107
	v_exp_f32_e32 v105, v105
	v_exp_f32_e32 v109, v109
	v_mul_f32_e32 v110, v87, v117
	v_fmac_f32_e32 v110, v83, v121
	v_add_f32_e32 v105, 1.0, v105
	v_add_f32_e32 v109, 1.0, v109
	v_rcp_f32_e32 v105, v105
	v_rcp_f32_e32 v109, v109
	v_fmac_f32_e32 v110, v91, v163
	v_add_f32_e32 v110, v95, v110
	v_mul_f32_e32 v101, v101, v105
	v_mul_f32_e32 v105, v107, v109
	v_mul_f32_e32 v107, v86, v116
	v_fmac_f32_e32 v107, v82, v120
	v_fmac_f32_e32 v107, v90, v162
	v_add_f32_e32 v107, v94, v107
	v_mul_f32_e32 v109, 0xbfb8aa3b, v107
	v_mul_f32_e32 v111, 0xbfb8aa3b, v110
	v_exp_f32_e32 v109, v109
	v_exp_f32_e32 v111, v111
	ds_read_b128 v[168:171], v100 offset:544
	s_waitcnt lgkmcnt(1)
	v_mul_f32_e32 v114, v72, v164
	v_add_f32_e32 v109, 1.0, v109
	v_add_f32_e32 v111, 1.0, v111
	v_rcp_f32_e32 v109, v109
	v_rcp_f32_e32 v111, v111
	v_fmac_f32_e32 v114, v64, v122
	s_waitcnt lgkmcnt(0)
	v_fmac_f32_e32 v114, v68, v168
	v_add_f32_e32 v114, v76, v114
	v_mul_f32_e32 v115, 0xbfb8aa3b, v114
	v_exp_f32_e32 v115, v115
	v_mul_f32_e32 v107, v107, v109
	v_mul_f32_e32 v109, v110, v111
	v_mul_f32_e32 v111, v73, v165
	v_fmac_f32_e32 v111, v65, v123
	v_fmac_f32_e32 v111, v69, v169
	v_add_f32_e32 v111, v77, v111
	v_add_f32_e32 v110, 1.0, v115
	v_mul_f32_e32 v115, 0xbfb8aa3b, v111
	v_rcp_f32_e32 v110, v110
	v_exp_f32_e32 v115, v115
	v_mul_f32_e32 v117, v75, v167
	v_fmac_f32_e32 v117, v67, v125
	v_mul_f32_e32 v110, v114, v110
	v_add_f32_e32 v114, 1.0, v115
	v_mul_f32_e32 v115, v74, v166
	v_fmac_f32_e32 v115, v66, v124
	v_fmac_f32_e32 v115, v70, v170
	v_add_f32_e32 v115, v78, v115
	v_fmac_f32_e32 v117, v71, v171
	v_mul_f32_e32 v116, 0xbfb8aa3b, v115
	v_add_f32_e32 v117, v79, v117
	v_rcp_f32_e32 v114, v114
	v_exp_f32_e32 v116, v116
	v_mul_f32_e32 v118, 0xbfb8aa3b, v117
	v_exp_f32_e32 v118, v118
	ds_read_b128 v[172:175], v100 offset:256
	ds_read_b128 v[178:181], v100 offset:272
	v_mul_f32_e32 v111, v111, v114
	v_add_f32_e32 v114, 1.0, v116
	v_rcp_f32_e32 v114, v114
	v_add_f32_e32 v116, 1.0, v118
	v_rcp_f32_e32 v116, v116
	s_waitcnt lgkmcnt(0)
	v_mul_f32_e32 v110, v178, v110
	v_mul_f32_e32 v111, v179, v111
	v_mul_f32_e32 v114, v115, v114
	v_mul_f32_e32 v118, v180, v114
	v_mul_f32_e32 v114, v117, v116
	v_cvt_pk_bf16_f32 v116, v110, v111
	v_add_u32_e32 v99, v99, v112
	v_mov_b64_e32 v[110:111], s[52:53]
	v_mad_i64_i32 v[110:111], s[6:7], v99, s30, v[110:111]
	v_mul_f32_e32 v117, v181, v114
	v_lshl_add_u64 v[110:111], v[96:97], 1, v[110:111]
	v_mul_f32_e32 v101, v172, v101
	v_mul_f32_e32 v105, v173, v105
	v_mul_f32_e32 v107, v174, v107
	v_mul_f32_e32 v109, v175, v109
	v_cvt_pk_bf16_f32 v114, v101, v105
	v_cvt_pk_bf16_f32 v115, v107, v109
	v_cvt_pk_bf16_f32 v117, v118, v117
	global_store_dwordx4 v[110:111], v[114:117], off
.LBB0_2009:
	s_or_b64 exec, exec, s[0:1]
	v_or_b32_e32 v109, 32, v106
	v_mul_u32_u24_e32 v99, 0x210, v109
	v_add3_u32 v99, v102, v99, v108
	v_add_u32_e32 v101, v98, v109
	v_add_u32_e32 v105, 0xfffffdf0, v99
	v_cmp_lt_i32_e64 s[0:1], v101, v113
	s_and_saveexec_b64 s[6:7], s[0:1]
	s_cbranch_execz .LBB0_2011
	ds_read_b128 v[114:117], v99
	ds_read_b128 v[118:121], v105
	ds_read_b128 v[122:125], v105 offset:16
	ds_read_b128 v[160:163], v99 offset:528
	ds_read_b128 v[164:167], v99 offset:16
	s_waitcnt lgkmcnt(4)
	v_mul_f32_e32 v107, v84, v114
	v_mul_f32_e32 v111, v85, v115
	s_waitcnt lgkmcnt(3)
	v_fmac_f32_e32 v107, v80, v118
	v_fmac_f32_e32 v111, v81, v119
	s_waitcnt lgkmcnt(1)
	v_fmac_f32_e32 v107, v88, v160
	v_fmac_f32_e32 v111, v89, v161
	v_add_f32_e32 v107, v92, v107
	v_add_f32_e32 v111, v93, v111
	v_mul_f32_e32 v110, 0xbfb8aa3b, v107
	v_mul_f32_e32 v114, 0xbfb8aa3b, v111
	v_exp_f32_e32 v110, v110
	v_exp_f32_e32 v114, v114
	v_mul_f32_e32 v115, v87, v117
	v_fmac_f32_e32 v115, v83, v121
	v_add_f32_e32 v110, 1.0, v110
	v_add_f32_e32 v114, 1.0, v114
	v_rcp_f32_e32 v110, v110
	v_rcp_f32_e32 v114, v114
	ds_read_b128 v[168:171], v99 offset:544
	v_fmac_f32_e32 v115, v91, v163
	v_mul_f32_e32 v107, v107, v110
	v_mul_f32_e32 v110, v111, v114
	v_mul_f32_e32 v111, v86, v116
	v_fmac_f32_e32 v111, v82, v120
	v_fmac_f32_e32 v111, v90, v162
	v_add_f32_e32 v111, v94, v111
	v_add_f32_e32 v115, v95, v115
	v_mul_f32_e32 v114, 0xbfb8aa3b, v111
	v_mul_f32_e32 v116, 0xbfb8aa3b, v115
	v_exp_f32_e32 v114, v114
	v_exp_f32_e32 v116, v116
	s_waitcnt lgkmcnt(1)
	v_mul_f32_e32 v117, v72, v164
	v_fmac_f32_e32 v117, v64, v122
	s_waitcnt lgkmcnt(0)
	v_fmac_f32_e32 v117, v68, v168
	v_add_f32_e32 v117, v76, v117
	v_add_f32_e32 v114, 1.0, v114
	v_add_f32_e32 v116, 1.0, v116
	v_mul_f32_e32 v118, 0xbfb8aa3b, v117
	v_rcp_f32_e32 v114, v114
	v_rcp_f32_e32 v116, v116
	v_exp_f32_e32 v118, v118
	ds_read_b128 v[172:175], v99 offset:256
	ds_read_b128 v[178:181], v99 offset:272
	v_mul_f32_e32 v111, v111, v114
	v_mul_f32_e32 v114, v115, v116
	v_add_f32_e32 v115, 1.0, v118
	v_mul_f32_e32 v116, v73, v165
	v_rcp_f32_e32 v115, v115
	v_fmac_f32_e32 v116, v65, v123
	v_fmac_f32_e32 v116, v69, v169
	v_add_f32_e32 v116, v77, v116
	v_mul_f32_e32 v118, 0xbfb8aa3b, v116
	v_exp_f32_e32 v118, v118
	s_waitcnt lgkmcnt(1)
	v_mul_f32_e32 v119, v175, v114
	v_mul_f32_e32 v114, v117, v115
	v_mul_f32_e32 v115, v74, v166
	v_fmac_f32_e32 v115, v66, v124
	v_mul_f32_e32 v120, v75, v167
	v_fmac_f32_e32 v115, v70, v170
	v_fmac_f32_e32 v120, v67, v125
	v_add_f32_e32 v115, v78, v115
	v_fmac_f32_e32 v120, v71, v171
	s_waitcnt lgkmcnt(0)
	v_mul_f32_e32 v117, v178, v114
	v_add_f32_e32 v114, 1.0, v118
	v_mul_f32_e32 v118, 0xbfb8aa3b, v115
	v_add_f32_e32 v120, v79, v120
	v_rcp_f32_e32 v114, v114
	v_exp_f32_e32 v118, v118
	v_mul_f32_e32 v121, 0xbfb8aa3b, v120
	v_exp_f32_e32 v121, v121
	v_mul_f32_e32 v114, v116, v114
	v_add_f32_e32 v116, 1.0, v118
	v_rcp_f32_e32 v116, v116
	v_add_f32_e32 v118, 1.0, v121
	v_rcp_f32_e32 v118, v118
	v_mul_f32_e32 v121, v179, v114
	v_mul_f32_e32 v114, v115, v116
	v_mul_f32_e32 v110, v173, v110
	v_mul_f32_e32 v111, v174, v111
	v_mul_f32_e32 v122, v180, v114
	v_mul_f32_e32 v114, v120, v118
	v_mul_f32_e32 v107, v172, v107
	v_mul_f32_e32 v118, v181, v114
	v_cvt_pk_bf16_f32 v114, v107, v110
	v_cvt_pk_bf16_f32 v115, v111, v119
	v_add_u32_e32 v101, v101, v112
	v_mov_b64_e32 v[110:111], s[52:53]
	v_mad_i64_i32 v[110:111], s[0:1], v101, s30, v[110:111]
	v_lshl_add_u64 v[110:111], v[96:97], 1, v[110:111]
	v_cvt_pk_bf16_f32 v116, v117, v121
	v_cvt_pk_bf16_f32 v117, v122, v118
	global_store_dwordx4 v[110:111], v[114:117], off
.LBB0_2011:
	s_or_b64 exec, exec, s[6:7]
	v_or_b32_e32 v110, 64, v106
	v_mul_u32_u24_e32 v101, 0x210, v110
	v_add3_u32 v101, v102, v101, v108
	v_add_u32_e32 v111, v98, v110
	v_add_u32_e32 v107, 0xfffffdf0, v101
	v_cmp_lt_i32_e64 s[0:1], v111, v113
	s_and_saveexec_b64 s[6:7], s[0:1]
	s_cbranch_execz .LBB0_2013
	ds_read_b128 v[114:117], v101
	ds_read_b128 v[118:121], v107
	ds_read_b128 v[122:125], v107 offset:16
	ds_read_b128 v[160:163], v101 offset:528
	ds_read_b128 v[164:167], v101 offset:16
	s_waitcnt lgkmcnt(4)
	v_mul_f32_e32 v115, v85, v115
	s_waitcnt lgkmcnt(3)
	v_fmac_f32_e32 v115, v81, v119
	v_mul_f32_e32 v114, v84, v114
	s_waitcnt lgkmcnt(1)
	v_fmac_f32_e32 v115, v89, v161
	v_add_f32_e32 v115, v93, v115
	v_mul_f32_e32 v119, 0xbfb8aa3b, v115
	v_fmac_f32_e32 v114, v80, v118
	v_exp_f32_e32 v119, v119
	v_fmac_f32_e32 v114, v88, v160
	v_add_f32_e32 v114, v92, v114
	v_mul_f32_e32 v118, 0xbfb8aa3b, v114
	v_exp_f32_e32 v118, v118
	v_add_f32_e32 v119, 1.0, v119
	v_rcp_f32_e32 v119, v119
	v_mul_f32_e32 v117, v87, v117
	v_fmac_f32_e32 v117, v83, v121
	v_fmac_f32_e32 v117, v91, v163
	v_add_f32_e32 v118, 1.0, v118
	v_add_f32_e32 v117, v95, v117
	v_rcp_f32_e32 v118, v118
	v_mul_f32_e32 v115, v115, v119
	v_mul_f32_e32 v116, v86, v116
	v_mul_f32_e32 v119, 0xbfb8aa3b, v117
	v_fmac_f32_e32 v116, v82, v120
	v_exp_f32_e32 v119, v119
	ds_read_b128 v[168:171], v101 offset:544
	v_fmac_f32_e32 v116, v90, v162
	v_add_f32_e32 v116, v94, v116
	v_mul_f32_e32 v114, v114, v118
	v_mul_f32_e32 v118, 0xbfb8aa3b, v116
	v_exp_f32_e32 v118, v118
	v_add_f32_e32 v119, 1.0, v119
	s_waitcnt lgkmcnt(1)
	v_mul_f32_e32 v120, v72, v164
	v_rcp_f32_e32 v119, v119
	v_fmac_f32_e32 v120, v64, v122
	s_waitcnt lgkmcnt(0)
	v_fmac_f32_e32 v120, v68, v168
	v_add_f32_e32 v120, v76, v120
	v_add_f32_e32 v118, 1.0, v118
	v_mul_f32_e32 v121, 0xbfb8aa3b, v120
	v_rcp_f32_e32 v118, v118
	v_exp_f32_e32 v121, v121
	v_mul_f32_e32 v117, v117, v119
	v_mul_f32_e32 v119, v73, v165
	v_fmac_f32_e32 v119, v65, v123
	v_fmac_f32_e32 v119, v69, v169
	v_add_f32_e32 v119, v77, v119
	v_mul_f32_e32 v116, v116, v118
	v_add_f32_e32 v118, 1.0, v121
	v_mul_f32_e32 v121, 0xbfb8aa3b, v119
	v_rcp_f32_e32 v118, v118
	v_exp_f32_e32 v121, v121
	v_mul_f32_e32 v123, v75, v167
	v_fmac_f32_e32 v123, v67, v125
	v_mul_f32_e32 v118, v120, v118
	v_add_f32_e32 v120, 1.0, v121
	v_mul_f32_e32 v121, v74, v166
	v_fmac_f32_e32 v121, v66, v124
	v_fmac_f32_e32 v121, v70, v170
	v_fmac_f32_e32 v123, v71, v171
	v_add_f32_e32 v121, v78, v121
	v_add_f32_e32 v123, v79, v123
	v_mul_f32_e32 v122, 0xbfb8aa3b, v121
	v_mul_f32_e32 v124, 0xbfb8aa3b, v123
	v_rcp_f32_e32 v120, v120
	v_exp_f32_e32 v122, v122
	v_exp_f32_e32 v124, v124
	ds_read_b128 v[172:175], v101 offset:256
	ds_read_b128 v[178:181], v101 offset:272
	v_mul_f32_e32 v119, v119, v120
	v_add_f32_e32 v120, 1.0, v122
	v_add_f32_e32 v122, 1.0, v124
	v_rcp_f32_e32 v120, v120
	v_rcp_f32_e32 v122, v122
	s_waitcnt lgkmcnt(1)
	v_mul_f32_e32 v114, v172, v114
	v_mul_f32_e32 v115, v173, v115
	v_mul_f32_e32 v116, v174, v116
	s_waitcnt lgkmcnt(0)
	v_mul_f32_e32 v118, v178, v118
	v_mul_f32_e32 v119, v179, v119
	v_mul_f32_e32 v117, v175, v117
	v_cvt_pk_bf16_f32 v114, v114, v115
	v_cvt_pk_bf16_f32 v115, v116, v117
	v_cvt_pk_bf16_f32 v116, v118, v119
	v_add_u32_e32 v111, v111, v112
	v_mov_b64_e32 v[118:119], s[52:53]
	v_mad_i64_i32 v[118:119], s[0:1], v111, s30, v[118:119]
	v_mul_f32_e32 v120, v121, v120
	v_mul_f32_e32 v121, v123, v122
	v_lshl_add_u64 v[118:119], v[96:97], 1, v[118:119]
	v_mul_f32_e32 v120, v180, v120
	v_mul_f32_e32 v121, v181, v121
	v_cvt_pk_bf16_f32 v117, v120, v121
	global_store_dwordx4 v[118:119], v[114:117], off
.LBB0_2013:
	s_or_b64 exec, exec, s[6:7]
	v_or_b32_e32 v111, 0x60, v106
	v_mul_u32_u24_e32 v114, 0x210, v111
	v_add_u32_e32 v98, v98, v111
	v_cmp_ne_u32_e64 s[0:1], 31, v106
	v_add3_u32 v102, v102, v114, v108
	v_cmp_lt_i32_e64 s[6:7], v98, v113
	v_add_u32_e32 v108, 0xfffffdf0, v102
	s_and_b64 s[34:35], s[0:1], s[6:7]
	s_and_saveexec_b64 s[6:7], s[34:35]
	s_cbranch_execz .LBB0_2015
	ds_read_b128 v[114:117], v102
	ds_read_b128 v[118:121], v108
	ds_read_b128 v[122:125], v108 offset:16
	ds_read_b128 v[160:163], v102 offset:528
	ds_read_b128 v[164:167], v102 offset:16
	ds_read_b128 v[168:171], v102 offset:544
	s_waitcnt lgkmcnt(5)
	v_mul_f32_e32 v84, v84, v114
	v_mul_f32_e32 v85, v85, v115
	s_waitcnt lgkmcnt(4)
	v_fmac_f32_e32 v84, v80, v118
	s_waitcnt lgkmcnt(1)
	v_mul_f32_e32 v72, v72, v164
	v_fmac_f32_e32 v72, v64, v122
	s_waitcnt lgkmcnt(0)
	v_fmac_f32_e32 v72, v68, v168
	v_add_f32_e32 v64, v76, v72
	v_mul_f32_e32 v68, 0xbfb8aa3b, v64
	v_exp_f32_e32 v68, v68
	v_fmac_f32_e32 v85, v81, v119
	v_mul_f32_e32 v73, v73, v165
	v_fmac_f32_e32 v84, v88, v160
	v_fmac_f32_e32 v85, v89, v161
	v_fmac_f32_e32 v73, v65, v123
	v_add_f32_e32 v80, v92, v84
	v_add_f32_e32 v81, v93, v85
	v_fmac_f32_e32 v73, v69, v169
	v_mul_f32_e32 v84, 0xbfb8aa3b, v80
	v_mul_f32_e32 v85, 0xbfb8aa3b, v81
	v_add_f32_e32 v68, 1.0, v68
	v_add_f32_e32 v65, v77, v73
	v_exp_f32_e32 v84, v84
	v_exp_f32_e32 v85, v85
	ds_read_b128 v[172:175], v102 offset:256
	ds_read_b128 v[178:181], v102 offset:272
	v_rcp_f32_e32 v68, v68
	v_mul_f32_e32 v69, 0xbfb8aa3b, v65
	v_exp_f32_e32 v69, v69
	v_add_f32_e32 v84, 1.0, v84
	v_add_f32_e32 v85, 1.0, v85
	v_mul_f32_e32 v64, v64, v68
	v_rcp_f32_e32 v84, v84
	v_rcp_f32_e32 v85, v85
	s_waitcnt lgkmcnt(0)
	v_mul_f32_e32 v68, v178, v64
	v_add_f32_e32 v64, 1.0, v69
	v_mul_f32_e32 v69, v74, v166
	v_fmac_f32_e32 v69, v66, v124
	v_fmac_f32_e32 v69, v70, v170
	v_mul_f32_e32 v70, v75, v167
	v_fmac_f32_e32 v70, v67, v125
	v_mul_f32_e32 v80, v80, v84
	v_mul_f32_e32 v81, v81, v85
	v_mul_f32_e32 v84, v86, v116
	v_mul_f32_e32 v85, v87, v117
	v_add_f32_e32 v66, v78, v69
	v_fmac_f32_e32 v70, v71, v171
	v_fmac_f32_e32 v84, v82, v120
	v_fmac_f32_e32 v85, v83, v121
	v_mul_f32_e32 v69, 0xbfb8aa3b, v66
	v_add_f32_e32 v67, v79, v70
	v_fmac_f32_e32 v84, v90, v162
	v_fmac_f32_e32 v85, v91, v163
	v_rcp_f32_e32 v64, v64
	v_exp_f32_e32 v69, v69
	v_mul_f32_e32 v70, 0xbfb8aa3b, v67
	v_add_f32_e32 v82, v94, v84
	v_add_f32_e32 v83, v95, v85
	v_exp_f32_e32 v70, v70
	v_mul_f32_e32 v84, 0xbfb8aa3b, v82
	v_mul_f32_e32 v85, 0xbfb8aa3b, v83
	v_exp_f32_e32 v84, v84
	v_exp_f32_e32 v85, v85
	v_mul_f32_e32 v64, v65, v64
	v_add_f32_e32 v65, 1.0, v69
	v_rcp_f32_e32 v65, v65
	v_add_f32_e32 v69, 1.0, v70
	v_rcp_f32_e32 v69, v69
	v_add_f32_e32 v84, 1.0, v84
	v_add_f32_e32 v85, 1.0, v85
	v_rcp_f32_e32 v84, v84
	v_rcp_f32_e32 v85, v85
	v_mul_f32_e32 v70, v179, v64
	v_mul_f32_e32 v64, v66, v65
	v_mul_f32_e32 v71, v180, v64
	v_mul_f32_e32 v64, v67, v69
	v_cvt_pk_bf16_f32 v66, v68, v70
	v_add_u32_e32 v70, v98, v112
	v_mov_b64_e32 v[68:69], s[52:53]
	v_mad_i64_i32 v[68:69], s[34:35], v70, s30, v[68:69]
	v_mul_f32_e32 v72, v82, v84
	v_mul_f32_e32 v76, v83, v85
	v_mul_f32_e32 v67, v181, v64
	v_lshl_add_u64 v[68:69], v[96:97], 1, v[68:69]
	v_mul_f32_e32 v80, v172, v80
	v_mul_f32_e32 v81, v173, v81
	v_mul_f32_e32 v72, v174, v72
	v_mul_f32_e32 v73, v175, v76
	v_cvt_pk_bf16_f32 v64, v80, v81
	v_cvt_pk_bf16_f32 v65, v72, v73
	v_cvt_pk_bf16_f32 v67, v71, v67
	global_store_dwordx4 v[68:69], v[64:67], off
.LBB0_2015:
	s_or_b64 exec, exec, s[6:7]
	s_barrier
	ds_write_b128 v132, v[60:63]
	ds_write_b128 v132, v[56:59] offset:64
	ds_write_b128 v132, v[52:55] offset:8448
	ds_write_b128 v132, v[48:51] offset:8512
	ds_write_b128 v132, v[44:47] offset:16896
	ds_write_b128 v132, v[40:43] offset:16960
	ds_write_b128 v132, v[36:39] offset:25344
	ds_write_b128 v132, v[32:35] offset:25408
	ds_write_b128 v132, v[28:31] offset:33792
	ds_write_b128 v132, v[24:27] offset:33856
	ds_write_b128 v132, v[20:23] offset:42240
	ds_write_b128 v132, v[16:19] offset:42304
	ds_write_b128 v132, v[12:15] offset:50688
	ds_write_b128 v132, v[8:11] offset:50752
	ds_write_b128 v132, v[4:7] offset:59136
	ds_write_b128 v132, v[0:3] offset:59200
	s_waitcnt lgkmcnt(0)
	s_barrier
	s_and_saveexec_b64 s[6:7], vcc
	s_xor_b64 s[6:7], exec, s[6:7]
	v_add_u32_e32 v0, 0xffffff78, v103
	v_mul_hi_u32 v1, v0, s24
	v_lshrrev_b32_e32 v1, 1, v1
	v_lshl_add_u32 v34, v1, 8, v159
	v_lshl_add_u32 v1, v1, 1, v1
	v_sub_u32_e32 v32, v0, v1
	s_or_saveexec_b64 s[6:7], s[6:7]
	v_mov_b32_e32 v35, 0x100
	s_xor_b64 exec, exec, s[6:7]
	v_mul_hi_i32 v0, v103, s16
	v_lshrrev_b32_e32 v1, 31, v0
	v_ashrrev_i32_e32 v0, 3, v0
	v_add_u32_e32 v0, v0, v1
	v_lshlrev_b32_e32 v34, 11, v0
	v_lshl_add_u32 v0, v0, 4, v0
	v_sub_u32_e32 v32, v103, v0
	v_mov_b32_e32 v35, 0x800
	s_or_b64 exec, exec, s[6:7]
	v_or_b32_e32 v0, 64, v96
	v_ashrrev_i32_e32 v1, 31, v0
	v_lshlrev_b64 v[12:13], 2, v[0:1]
	v_lshl_add_u64 v[4:5], s[8:9], 0, v[12:13]
	v_lshl_add_u64 v[8:9], s[12:13], 0, v[12:13]
	v_lshl_add_u64 v[14:15], s[14:15], 0, v[12:13]
	v_lshl_add_u64 v[36:37], s[10:11], 0, v[12:13]
	s_waitcnt vmcnt(0)
	v_mov_b64_e32 v[16:17], v[200:201]
	v_mov_b64_e32 v[18:19], v[202:203]
	v_mov_b64_e32 v[0:1], v[204:205]
	v_mov_b64_e32 v[2:3], v[206:207]
	v_mov_b64_e32 v[20:21], v[208:209]
	v_mov_b64_e32 v[22:23], v[210:211]
	s_nop 0
	v_mov_b64_e32 v[4:5], v[212:213]
	v_mov_b64_e32 v[6:7], v[214:215]
	v_mov_b64_e32 v[24:25], v[216:217]
	v_mov_b64_e32 v[26:27], v[218:219]
	s_nop 0
	v_mov_b64_e32 v[8:9], v[220:221]
	v_mov_b64_e32 v[10:11], v[222:223]
	v_mov_b64_e32 v[28:29], v[224:225]
	v_mov_b64_e32 v[30:31], v[226:227]
	s_nop 0
	v_mov_b64_e32 v[12:13], v[228:229]
	v_mov_b64_e32 v[14:15], v[230:231]
	v_mad_u64_u32 v[32:33], s[6:7], v32, s26, -1
	v_add_u32_e32 v33, v32, v106
	v_cmp_lt_i32_e32 vcc, v33, v35
	s_and_b64 s[20:21], s[20:21], vcc
	s_and_saveexec_b64 s[6:7], s[20:21]
	s_cbranch_execz .LBB0_2021
	ds_read_b128 v[36:39], v100
	ds_read_b128 v[40:43], v104
	ds_read_b128 v[44:47], v104 offset:16
	ds_read_b128 v[48:51], v100 offset:528
	ds_read_b128 v[52:55], v100 offset:16
	s_waitcnt lgkmcnt(4)
	v_mul_f32_e32 v37, v21, v37
	s_waitcnt lgkmcnt(3)
	v_fmac_f32_e32 v37, v17, v41
	v_mul_f32_e32 v36, v20, v36
	s_waitcnt lgkmcnt(1)
	v_fmac_f32_e32 v37, v25, v49
	v_add_f32_e32 v37, v29, v37
	v_mul_f32_e32 v41, 0xbfb8aa3b, v37
	v_fmac_f32_e32 v36, v16, v40
	v_exp_f32_e32 v41, v41
	v_fmac_f32_e32 v36, v24, v48
	v_add_f32_e32 v36, v28, v36
	v_mul_f32_e32 v40, 0xbfb8aa3b, v36
	v_exp_f32_e32 v40, v40
	v_add_f32_e32 v41, 1.0, v41
	v_rcp_f32_e32 v41, v41
	v_mul_f32_e32 v39, v23, v39
	v_fmac_f32_e32 v39, v19, v43
	v_fmac_f32_e32 v39, v27, v51
	v_add_f32_e32 v40, 1.0, v40
	v_add_f32_e32 v39, v31, v39
	v_rcp_f32_e32 v40, v40
	v_mul_f32_e32 v37, v37, v41
	v_mul_f32_e32 v38, v22, v38
	v_mul_f32_e32 v41, 0xbfb8aa3b, v39
	v_fmac_f32_e32 v38, v18, v42
	v_exp_f32_e32 v41, v41
	ds_read_b128 v[56:59], v100 offset:544
	v_fmac_f32_e32 v38, v26, v50
	v_add_f32_e32 v38, v30, v38
	v_mul_f32_e32 v36, v36, v40
	v_mul_f32_e32 v40, 0xbfb8aa3b, v38
	v_exp_f32_e32 v40, v40
	v_add_f32_e32 v41, 1.0, v41
	s_waitcnt lgkmcnt(1)
	v_mul_f32_e32 v42, v4, v52
	v_rcp_f32_e32 v41, v41
	v_fmac_f32_e32 v42, v0, v44
	s_waitcnt lgkmcnt(0)
	v_fmac_f32_e32 v42, v8, v56
	v_add_f32_e32 v42, v12, v42
	v_add_f32_e32 v40, 1.0, v40
	v_mul_f32_e32 v43, 0xbfb8aa3b, v42
	v_rcp_f32_e32 v40, v40
	v_exp_f32_e32 v43, v43
	v_mul_f32_e32 v39, v39, v41
	v_mul_f32_e32 v41, v5, v53
	v_fmac_f32_e32 v41, v1, v45
	v_fmac_f32_e32 v41, v9, v57
	v_add_f32_e32 v41, v13, v41
	v_mul_f32_e32 v38, v38, v40
	v_add_f32_e32 v40, 1.0, v43
	v_mul_f32_e32 v43, 0xbfb8aa3b, v41
	v_rcp_f32_e32 v40, v40
	v_exp_f32_e32 v43, v43
	v_mul_f32_e32 v45, v7, v55
	v_fmac_f32_e32 v45, v3, v47
	v_mul_f32_e32 v40, v42, v40
	v_add_f32_e32 v42, 1.0, v43
	v_mul_f32_e32 v43, v6, v54
	v_fmac_f32_e32 v43, v2, v46
	v_fmac_f32_e32 v43, v10, v58
	v_fmac_f32_e32 v45, v11, v59
	v_add_f32_e32 v43, v14, v43
	v_add_f32_e32 v45, v15, v45
	v_mul_f32_e32 v44, 0xbfb8aa3b, v43
	v_mul_f32_e32 v46, 0xbfb8aa3b, v45
	v_rcp_f32_e32 v42, v42
	v_exp_f32_e32 v44, v44
	v_exp_f32_e32 v46, v46
	ds_read_b128 v[60:63], v100 offset:256
	ds_read_b128 v[64:67], v100 offset:272
	v_mul_f32_e32 v41, v41, v42
	v_add_f32_e32 v42, 1.0, v44
	v_add_f32_e32 v44, 1.0, v46
	v_rcp_f32_e32 v42, v42
	v_rcp_f32_e32 v44, v44
	s_waitcnt lgkmcnt(1)
	v_mul_f32_e32 v36, v60, v36
	v_mul_f32_e32 v37, v61, v37
	v_mul_f32_e32 v38, v62, v38
	s_waitcnt lgkmcnt(0)
	v_mul_f32_e32 v40, v64, v40
	v_mul_f32_e32 v41, v65, v41
	v_mul_f32_e32 v39, v63, v39
	v_cvt_pk_bf16_f32 v36, v36, v37
	v_cvt_pk_bf16_f32 v37, v38, v39
	v_cvt_pk_bf16_f32 v38, v40, v41
	v_add_u32_e32 v33, v33, v34
	v_mov_b64_e32 v[40:41], s[52:53]
	v_mad_i64_i32 v[40:41], s[20:21], v33, s30, v[40:41]
	v_mul_f32_e32 v42, v43, v42
	v_mul_f32_e32 v43, v45, v44
	v_lshl_add_u64 v[40:41], v[96:97], 1, v[40:41]
	v_mul_f32_e32 v42, v66, v42
	v_mul_f32_e32 v43, v67, v43
	v_cvt_pk_bf16_f32 v39, v42, v43
	global_store_dwordx4 v[40:41], v[36:39], off offset:128
.LBB0_2021:
	s_or_b64 exec, exec, s[6:7]
	v_add_u32_e32 v33, v32, v109
	v_cmp_lt_i32_e32 vcc, v33, v35
	s_and_saveexec_b64 s[6:7], vcc
	s_cbranch_execz .LBB0_2023
	ds_read_b128 v[36:39], v99
	ds_read_b128 v[40:43], v105
	ds_read_b128 v[44:47], v105 offset:16
	ds_read_b128 v[48:51], v99 offset:528
	ds_read_b128 v[52:55], v99 offset:16
	s_waitcnt lgkmcnt(4)
	v_mul_f32_e32 v37, v21, v37
	s_waitcnt lgkmcnt(3)
	v_fmac_f32_e32 v37, v17, v41
	v_mul_f32_e32 v36, v20, v36
	s_waitcnt lgkmcnt(1)
	v_fmac_f32_e32 v37, v25, v49
	v_add_f32_e32 v37, v29, v37
	v_mul_f32_e32 v41, 0xbfb8aa3b, v37
	v_fmac_f32_e32 v36, v16, v40
	v_exp_f32_e32 v41, v41
	v_fmac_f32_e32 v36, v24, v48
	v_add_f32_e32 v36, v28, v36
	v_mul_f32_e32 v40, 0xbfb8aa3b, v36
	v_exp_f32_e32 v40, v40
	v_add_f32_e32 v41, 1.0, v41
	v_rcp_f32_e32 v41, v41
	v_mul_f32_e32 v39, v23, v39
	v_fmac_f32_e32 v39, v19, v43
	v_fmac_f32_e32 v39, v27, v51
	v_add_f32_e32 v40, 1.0, v40
	v_add_f32_e32 v39, v31, v39
	v_rcp_f32_e32 v40, v40
	v_mul_f32_e32 v37, v37, v41
	v_mul_f32_e32 v38, v22, v38
	v_mul_f32_e32 v41, 0xbfb8aa3b, v39
	v_fmac_f32_e32 v38, v18, v42
	v_exp_f32_e32 v41, v41
	ds_read_b128 v[56:59], v99 offset:544
	v_fmac_f32_e32 v38, v26, v50
	v_add_f32_e32 v38, v30, v38
	v_mul_f32_e32 v36, v36, v40
	v_mul_f32_e32 v40, 0xbfb8aa3b, v38
	v_exp_f32_e32 v40, v40
	v_add_f32_e32 v41, 1.0, v41
	s_waitcnt lgkmcnt(1)
	v_mul_f32_e32 v42, v4, v52
	v_rcp_f32_e32 v41, v41
	v_fmac_f32_e32 v42, v0, v44
	s_waitcnt lgkmcnt(0)
	v_fmac_f32_e32 v42, v8, v56
	v_add_f32_e32 v42, v12, v42
	v_add_f32_e32 v40, 1.0, v40
	v_mul_f32_e32 v43, 0xbfb8aa3b, v42
	v_rcp_f32_e32 v40, v40
	v_exp_f32_e32 v43, v43
	v_mul_f32_e32 v39, v39, v41
	v_mul_f32_e32 v41, v5, v53
	v_fmac_f32_e32 v41, v1, v45
	v_fmac_f32_e32 v41, v9, v57
	v_add_f32_e32 v41, v13, v41
	v_mul_f32_e32 v38, v38, v40
	v_add_f32_e32 v40, 1.0, v43
	v_mul_f32_e32 v43, 0xbfb8aa3b, v41
	v_rcp_f32_e32 v40, v40
	v_exp_f32_e32 v43, v43
	v_mul_f32_e32 v45, v7, v55
	v_fmac_f32_e32 v45, v3, v47
	v_mul_f32_e32 v40, v42, v40
	v_add_f32_e32 v42, 1.0, v43
	v_mul_f32_e32 v43, v6, v54
	v_fmac_f32_e32 v43, v2, v46
	v_fmac_f32_e32 v43, v10, v58
	v_fmac_f32_e32 v45, v11, v59
	v_add_f32_e32 v43, v14, v43
	v_add_f32_e32 v45, v15, v45
	v_mul_f32_e32 v44, 0xbfb8aa3b, v43
	v_mul_f32_e32 v46, 0xbfb8aa3b, v45
	v_rcp_f32_e32 v42, v42
	v_exp_f32_e32 v44, v44
	v_exp_f32_e32 v46, v46
	ds_read_b128 v[60:63], v99 offset:256
	ds_read_b128 v[64:67], v99 offset:272
	v_mul_f32_e32 v41, v41, v42
	v_add_f32_e32 v42, 1.0, v44
	v_add_f32_e32 v44, 1.0, v46
	v_rcp_f32_e32 v42, v42
	v_rcp_f32_e32 v44, v44
	s_waitcnt lgkmcnt(1)
	v_mul_f32_e32 v36, v60, v36
	v_mul_f32_e32 v37, v61, v37
	v_mul_f32_e32 v38, v62, v38
	s_waitcnt lgkmcnt(0)
	v_mul_f32_e32 v40, v64, v40
	v_mul_f32_e32 v41, v65, v41
	v_mul_f32_e32 v39, v63, v39
	v_cvt_pk_bf16_f32 v36, v36, v37
	v_cvt_pk_bf16_f32 v37, v38, v39
	v_cvt_pk_bf16_f32 v38, v40, v41
	v_add_u32_e32 v33, v33, v34
	v_mov_b64_e32 v[40:41], s[52:53]
	v_mad_i64_i32 v[40:41], s[20:21], v33, s30, v[40:41]
	v_mul_f32_e32 v42, v43, v42
	v_mul_f32_e32 v43, v45, v44
	v_lshl_add_u64 v[40:41], v[96:97], 1, v[40:41]
	v_mul_f32_e32 v42, v66, v42
	v_mul_f32_e32 v43, v67, v43
	v_cvt_pk_bf16_f32 v39, v42, v43
	global_store_dwordx4 v[40:41], v[36:39], off offset:128
.LBB0_2023:
	s_or_b64 exec, exec, s[6:7]
	v_add_u32_e32 v33, v32, v110
	v_cmp_lt_i32_e32 vcc, v33, v35
	s_and_saveexec_b64 s[6:7], vcc
	s_cbranch_execz .LBB0_2025
	ds_read_b128 v[36:39], v101
	ds_read_b128 v[40:43], v107
	ds_read_b128 v[44:47], v107 offset:16
	ds_read_b128 v[48:51], v101 offset:528
	ds_read_b128 v[52:55], v101 offset:16
	s_waitcnt lgkmcnt(4)
	v_mul_f32_e32 v37, v21, v37
	s_waitcnt lgkmcnt(3)
	v_fmac_f32_e32 v37, v17, v41
	v_mul_f32_e32 v36, v20, v36
	s_waitcnt lgkmcnt(1)
	v_fmac_f32_e32 v37, v25, v49
	v_add_f32_e32 v37, v29, v37
	v_mul_f32_e32 v41, 0xbfb8aa3b, v37
	v_fmac_f32_e32 v36, v16, v40
	v_exp_f32_e32 v41, v41
	v_fmac_f32_e32 v36, v24, v48
	v_add_f32_e32 v36, v28, v36
	v_mul_f32_e32 v40, 0xbfb8aa3b, v36
	v_exp_f32_e32 v40, v40
	v_add_f32_e32 v41, 1.0, v41
	v_rcp_f32_e32 v41, v41
	v_mul_f32_e32 v39, v23, v39
	v_fmac_f32_e32 v39, v19, v43
	v_fmac_f32_e32 v39, v27, v51
	v_add_f32_e32 v40, 1.0, v40
	v_add_f32_e32 v39, v31, v39
	v_rcp_f32_e32 v40, v40
	v_mul_f32_e32 v37, v37, v41
	v_mul_f32_e32 v38, v22, v38
	v_mul_f32_e32 v41, 0xbfb8aa3b, v39
	v_fmac_f32_e32 v38, v18, v42
	v_exp_f32_e32 v41, v41
	ds_read_b128 v[56:59], v101 offset:544
	v_fmac_f32_e32 v38, v26, v50
	v_add_f32_e32 v38, v30, v38
	v_mul_f32_e32 v36, v36, v40
	v_mul_f32_e32 v40, 0xbfb8aa3b, v38
	v_exp_f32_e32 v40, v40
	v_add_f32_e32 v41, 1.0, v41
	s_waitcnt lgkmcnt(1)
	v_mul_f32_e32 v42, v4, v52
	v_rcp_f32_e32 v41, v41
	v_fmac_f32_e32 v42, v0, v44
	s_waitcnt lgkmcnt(0)
	v_fmac_f32_e32 v42, v8, v56
	v_add_f32_e32 v42, v12, v42
	v_add_f32_e32 v40, 1.0, v40
	v_mul_f32_e32 v43, 0xbfb8aa3b, v42
	v_rcp_f32_e32 v40, v40
	v_exp_f32_e32 v43, v43
	v_mul_f32_e32 v39, v39, v41
	v_mul_f32_e32 v41, v5, v53
	v_fmac_f32_e32 v41, v1, v45
	v_fmac_f32_e32 v41, v9, v57
	v_add_f32_e32 v41, v13, v41
	v_mul_f32_e32 v38, v38, v40
	v_add_f32_e32 v40, 1.0, v43
	v_mul_f32_e32 v43, 0xbfb8aa3b, v41
	v_rcp_f32_e32 v40, v40
	v_exp_f32_e32 v43, v43
	v_mul_f32_e32 v45, v7, v55
	v_fmac_f32_e32 v45, v3, v47
	v_mul_f32_e32 v40, v42, v40
	v_add_f32_e32 v42, 1.0, v43
	v_mul_f32_e32 v43, v6, v54
	v_fmac_f32_e32 v43, v2, v46
	v_fmac_f32_e32 v43, v10, v58
	v_fmac_f32_e32 v45, v11, v59
	v_add_f32_e32 v43, v14, v43
	v_add_f32_e32 v45, v15, v45
	v_mul_f32_e32 v44, 0xbfb8aa3b, v43
	v_mul_f32_e32 v46, 0xbfb8aa3b, v45
	v_rcp_f32_e32 v42, v42
	v_exp_f32_e32 v44, v44
	v_exp_f32_e32 v46, v46
	ds_read_b128 v[60:63], v101 offset:256
	ds_read_b128 v[64:67], v101 offset:272
	v_mul_f32_e32 v41, v41, v42
	v_add_f32_e32 v42, 1.0, v44
	v_add_f32_e32 v44, 1.0, v46
	v_rcp_f32_e32 v42, v42
	v_rcp_f32_e32 v44, v44
	s_waitcnt lgkmcnt(1)
	v_mul_f32_e32 v36, v60, v36
	v_mul_f32_e32 v37, v61, v37
	v_mul_f32_e32 v38, v62, v38
	s_waitcnt lgkmcnt(0)
	v_mul_f32_e32 v40, v64, v40
	v_mul_f32_e32 v41, v65, v41
	v_mul_f32_e32 v39, v63, v39
	v_cvt_pk_bf16_f32 v36, v36, v37
	v_cvt_pk_bf16_f32 v37, v38, v39
	v_cvt_pk_bf16_f32 v38, v40, v41
	v_add_u32_e32 v33, v33, v34
	v_mov_b64_e32 v[40:41], s[52:53]
	v_mad_i64_i32 v[40:41], s[20:21], v33, s30, v[40:41]
	v_mul_f32_e32 v42, v43, v42
	v_mul_f32_e32 v43, v45, v44
	v_lshl_add_u64 v[40:41], v[96:97], 1, v[40:41]
	v_mul_f32_e32 v42, v66, v42
	v_mul_f32_e32 v43, v67, v43
	v_cvt_pk_bf16_f32 v39, v42, v43
	global_store_dwordx4 v[40:41], v[36:39], off offset:128
.LBB0_2025:
	s_or_b64 exec, exec, s[6:7]
	v_add_u32_e32 v32, v32, v111
	v_cmp_lt_i32_e32 vcc, v32, v35
	s_and_b64 s[6:7], s[0:1], vcc
	s_and_saveexec_b64 s[0:1], s[6:7]
	s_cbranch_execz .LBB0_1987
	ds_read_b128 v[36:39], v102
	ds_read_b128 v[40:43], v108
	ds_read_b128 v[44:47], v108 offset:16
	ds_read_b128 v[48:51], v102 offset:528
	ds_read_b128 v[52:55], v102 offset:16
	ds_read_b128 v[56:59], v102 offset:544
	s_waitcnt lgkmcnt(5)
	v_mul_f32_e32 v20, v20, v36
	v_mul_f32_e32 v21, v21, v37
	s_waitcnt lgkmcnt(4)
	v_fmac_f32_e32 v20, v16, v40
	s_waitcnt lgkmcnt(1)
	v_mul_f32_e32 v4, v4, v52
	v_fmac_f32_e32 v4, v0, v44
	s_waitcnt lgkmcnt(0)
	v_fmac_f32_e32 v4, v8, v56
	v_add_f32_e32 v0, v12, v4
	v_mul_f32_e32 v4, 0xbfb8aa3b, v0
	v_fmac_f32_e32 v21, v17, v41
	v_exp_f32_e32 v4, v4
	v_fmac_f32_e32 v20, v24, v48
	v_fmac_f32_e32 v21, v25, v49
	v_mul_f32_e32 v5, v5, v53
	v_add_f32_e32 v16, v28, v20
	v_add_f32_e32 v17, v29, v21
	v_fmac_f32_e32 v5, v1, v45
	v_mul_f32_e32 v20, 0xbfb8aa3b, v16
	v_mul_f32_e32 v21, 0xbfb8aa3b, v17
	v_fmac_f32_e32 v5, v9, v57
	v_exp_f32_e32 v20, v20
	v_exp_f32_e32 v21, v21
	v_add_f32_e32 v4, 1.0, v4
	v_add_f32_e32 v1, v13, v5
	ds_read_b128 v[60:63], v102 offset:256
	ds_read_b128 v[64:67], v102 offset:272
	v_rcp_f32_e32 v4, v4
	v_mul_f32_e32 v5, 0xbfb8aa3b, v1
	v_exp_f32_e32 v5, v5
	v_add_f32_e32 v20, 1.0, v20
	v_add_f32_e32 v21, 1.0, v21
	v_rcp_f32_e32 v20, v20
	v_rcp_f32_e32 v21, v21
	v_mul_f32_e32 v0, v0, v4
	s_waitcnt lgkmcnt(0)
	v_mul_f32_e32 v4, v64, v0
	v_add_f32_e32 v0, 1.0, v5
	v_mul_f32_e32 v5, v6, v54
	v_fmac_f32_e32 v5, v2, v46
	v_mul_f32_e32 v6, v7, v55
	v_fmac_f32_e32 v5, v10, v58
	v_fmac_f32_e32 v6, v3, v47
	v_mul_f32_e32 v16, v16, v20
	v_mul_f32_e32 v17, v17, v21
	v_mul_f32_e32 v20, v22, v38
	v_mul_f32_e32 v21, v23, v39
	v_add_f32_e32 v2, v14, v5
	v_fmac_f32_e32 v6, v11, v59
	v_fmac_f32_e32 v20, v18, v42
	v_fmac_f32_e32 v21, v19, v43
	v_mul_f32_e32 v5, 0xbfb8aa3b, v2
	v_add_f32_e32 v3, v15, v6
	v_fmac_f32_e32 v20, v26, v50
	v_fmac_f32_e32 v21, v27, v51
	v_rcp_f32_e32 v0, v0
	v_exp_f32_e32 v5, v5
	v_mul_f32_e32 v6, 0xbfb8aa3b, v3
	v_add_f32_e32 v18, v30, v20
	v_add_f32_e32 v19, v31, v21
	v_exp_f32_e32 v6, v6
	v_mul_f32_e32 v20, 0xbfb8aa3b, v18
	v_mul_f32_e32 v21, 0xbfb8aa3b, v19
	v_exp_f32_e32 v20, v20
	v_exp_f32_e32 v21, v21
	v_mul_f32_e32 v0, v1, v0
	v_add_f32_e32 v1, 1.0, v5
	v_rcp_f32_e32 v1, v1
	v_add_f32_e32 v5, 1.0, v6
	v_rcp_f32_e32 v5, v5
	v_add_f32_e32 v20, 1.0, v20
	v_add_f32_e32 v21, 1.0, v21
	v_rcp_f32_e32 v20, v20
	v_rcp_f32_e32 v21, v21
	v_mul_f32_e32 v6, v65, v0
	v_mul_f32_e32 v0, v2, v1
	v_mul_f32_e32 v7, v66, v0
	v_mul_f32_e32 v0, v3, v5
	v_cvt_pk_bf16_f32 v2, v4, v6
	v_add_u32_e32 v6, v32, v34
	v_mov_b64_e32 v[4:5], s[52:53]
	v_mad_i64_i32 v[4:5], s[6:7], v6, s30, v[4:5]
	v_mul_f32_e32 v8, v18, v20
	v_mul_f32_e32 v12, v19, v21
	v_mul_f32_e32 v3, v67, v0
	v_lshl_add_u64 v[4:5], v[96:97], 1, v[4:5]
	v_mul_f32_e32 v16, v60, v16
	v_mul_f32_e32 v17, v61, v17
	v_mul_f32_e32 v8, v62, v8
	v_mul_f32_e32 v9, v63, v12
	v_cvt_pk_bf16_f32 v0, v16, v17
	v_cvt_pk_bf16_f32 v1, v8, v9
	v_cvt_pk_bf16_f32 v3, v7, v3
	global_store_dwordx4 v[4:5], v[0:3], off offset:128
	s_branch .LBB0_1987
